# attention tile loops: packed f32 VALU (v_pk_add/v_pk_fma) replaced by scalar ops so the softmax VALU issues in the MFMA shadow
# speedup vs baseline: 1.0381x; 1.0381x over previous
; #define LAS __attribute__((address_space(3)))
; template <int DQK, int DV, int FLAGS, int qp, int kp, int vts, int op> ...
;     ...
;             __builtin_amdgcn_sched_barrier(0);
; #pragma unroll
;             for (int c = 0; c < ND0 / 2; ++c) {
;                 if (c + 1 < ND0 / 2) {
; #pragma unroll
;                     for (int i = 0; i < 2; ++i) { kf[(c + 1) & 1][2 * i] = *(const LAS bf16x8*)(kb + (2 * c + 2 + i) * 32); kf[(c + 1) & 1][2 * i + 1] = *(const LAS bf16x8*)(kb + 32 * KROW + (2 * c + 2 + i) * 32); }
;                 }
; #pragma unroll
;                 for (int i = 0; i < 2; ++i) {
;                     p0 = __builtin_amdgcn_mfma_f32_32x32x16_bf16(kf[c & 1][2 * i], qr[2 * c + i], p0, 0, 0, 0);
;                     p1 = __builtin_amdgcn_mfma_f32_32x32x16_bf16(kf[c & 1][2 * i + 1], qr[2 * c + i], p1, 0, 0, 0);
;                 }
;                 __builtin_amdgcn_sched_barrier(0);
;             }
;     ...
;             f32x2 rs2 = {0.f, 0.f};
; #pragma unroll
;             for (int r = 0; r < 16; ++r) { p0[r] = __builtin_amdgcn_exp2f(p0[r]); p1[r] = __builtin_amdgcn_exp2f(p1[r]); }
; #pragma unroll
;             for (int r = 0; r < 16; r += 2) { rs2 += (f32x2){p0[r], p0[r + 1]}; rs2 += (f32x2){p1[r], p1[r + 1]}; }
;             l += rs2.x + rs2.y;
;             bf16x8 pf[4];
;             pf[0] = pack_bf16x8(p0, 0); pf[1] = pack_bf16x8(p0, 8); pf[2] = pack_bf16x8(p1, 0); pf[3] = pack_bf16x8(p1, 8);
;             __builtin_amdgcn_sched_barrier(0);
; #pragma unroll
;             for (int d = 0; d < NDB; ++d) {
;                 if (d + 1 < NDB) {
; #pragma unroll
;                     for (int ks = 0; ks < 4; ++ks) vf[(d + 1) & 1][ks] = *(const LAS bf16x8*)(vb + (d + 1) * 32 * VROW + ks * 32);
;                 }
; #pragma unroll
;                 for (int ks = 0; ks < 4; ++ks) o[d] = __builtin_amdgcn_mfma_f32_32x32x16_bf16(vf[d & 1][ks], pf[ks], o[d], 0, 0, 0);
;                 __builtin_amdgcn_sched_barrier(0);
;             }
;         }
;         if (skip && more) ATT_GLOAD((FLAGS & AF_REV) ? t - 1 : t + 1);
;         if (more) ATT_LSTORE(cur ^ 1);
.Lr_top0:
	s_cmp_eq_u32 s3, 0
	s_cbranch_scc1 .Lr_gen0
	s_add_i32 s13, s3, 1
	s_cmp_ge_i32 s13, s20
	s_cbranch_scc1 .Lr_gen0
	s_add_i32 s12, s3, 1
	s_and_b32 s12, s12, 3
	s_mulk_i32 s12, 0x5800
	v_add_u32_e32 v206, s12, v246
	ds_read_b128 v[96:99], v206 offset:0
	ds_read_b128 v[100:103], v206 offset:832
	ds_read_b128 v[104:107], v206 offset:6656
	ds_read_b128 v[108:111], v206 offset:7488
	ds_read_b128 v[112:115], v206 offset:64
	ds_read_b128 v[116:119], v206 offset:896
	ds_read_b128 v[120:123], v206 offset:6720
	ds_read_b128 v[124:127], v206 offset:7552
	s_and_b32 s16, s3, 3
	s_mulk_i32 s16, 0x5800
	v_add_u32_e32 v207, s16, v247
	v_mfma_f32_16x16x32_bf16 v[32:35], v[152:155], v[214:217], v[32:35]
	v_mfma_f32_16x16x32_bf16 v[16:19], v[152:155], v[230:233], v[16:19]
	v_exp_f32_e32 v64, v64
	v_exp_f32_e32 v65, v65
	v_mfma_f32_16x16x32_bf16 v[36:39], v[156:159], v[214:217], v[36:39]
	v_mfma_f32_16x16x32_bf16 v[20:23], v[156:159], v[230:233], v[20:23]
	v_exp_f32_e32 v80, v80
	v_exp_f32_e32 v81, v81
	v_mov_b32_e32 v204, v64
	v_mov_b32_e32 v205, v65
	v_mfma_f32_16x16x32_bf16 v[40:43], v[160:163], v[214:217], v[40:43]
	v_mfma_f32_16x16x32_bf16 v[24:27], v[160:163], v[230:233], v[24:27]
	v_exp_f32_e32 v66, v66
	v_exp_f32_e32 v67, v67
	v_mov_b32_e32 v208, v80
	v_mov_b32_e32 v209, v81
	v_mfma_f32_16x16x32_bf16 v[44:47], v[164:167], v[214:217], v[44:47]
	v_mfma_f32_16x16x32_bf16 v[28:31], v[164:167], v[230:233], v[28:31]
	v_exp_f32_e32 v82, v82
	v_exp_f32_e32 v83, v83
	v_add_f32_e32 v204, v66, v204
	v_add_f32_e32 v205, v67, v205
	ds_read_b128 v[152:155], v207 offset:13312
	ds_read_b128 v[156:159], v207 offset:15616
	ds_read_b128 v[160:163], v207 offset:17920
	ds_read_b128 v[164:167], v207 offset:20224
	v_mfma_f32_16x16x32_bf16 v[32:35], v[188:191], v[218:221], v[32:35]
	v_mfma_f32_16x16x32_bf16 v[16:19], v[188:191], v[234:237], v[16:19]
	v_exp_f32_e32 v68, v68
	v_exp_f32_e32 v69, v69
	v_add_f32_e32 v208, v82, v208
	v_add_f32_e32 v209, v83, v209
	v_mfma_f32_16x16x32_bf16 v[36:39], v[192:195], v[218:221], v[36:39]
	v_mfma_f32_16x16x32_bf16 v[20:23], v[192:195], v[234:237], v[20:23]
	v_exp_f32_e32 v84, v84
	v_exp_f32_e32 v85, v85
	v_add_f32_e32 v204, v68, v204
	v_add_f32_e32 v205, v69, v205
	v_mfma_f32_16x16x32_bf16 v[40:43], v[196:199], v[218:221], v[40:43]
	v_mfma_f32_16x16x32_bf16 v[24:27], v[196:199], v[234:237], v[24:27]
	v_exp_f32_e32 v70, v70
	v_exp_f32_e32 v71, v71
	v_add_f32_e32 v208, v84, v208
	v_add_f32_e32 v209, v85, v209
	v_mfma_f32_16x16x32_bf16 v[44:47], v[200:203], v[218:221], v[44:47]
	v_mfma_f32_16x16x32_bf16 v[28:31], v[200:203], v[234:237], v[28:31]
	v_exp_f32_e32 v86, v86
	v_exp_f32_e32 v87, v87
	v_add_f32_e32 v204, v70, v204
	v_add_f32_e32 v205, v71, v205
	s_add_i32 s12, s3, 2
	s_cmp_ge_i32 s12, s2
	s_cbranch_scc1 .Lr_nols_s0
	s_and_b32 s16, s12, 3
	s_mulk_i32 s16, 0x5800
	s_waitcnt vmcnt(0)
	v_add_u32_e32 v56, s16, v14
	v_add_u32_e32 v57, s16, v174
	v_add_u32_e32 v58, s16, v172
	ds_write_b128 v56, v[140:143]
	ds_write_b128 v57, v[148:151] offset:13312
	s_and_saveexec_b64 s[14:15], s[10:11]
	ds_write_b128 v58, v[144:147]
	s_or_b64 exec, exec, s[14:15]
	s_add_i32 s12, s3, 3
	s_cmp_ge_i32 s12, s2
	s_cbranch_scc1 .Lr_nols_s0
	s_and_saveexec_b64 s[14:15], s[10:11]
	global_load_dwordx4 v[144:147], v[180:181], off
	s_or_b64 exec, exec, s[14:15]
	global_load_dwordx4 v[140:143], v[178:179], off
	global_load_dwordx4 v[148:151], v[176:177], off
	s_mov_b64 s[14:15], 0x80
	v_lshl_add_u64 v[176:177], v[176:177], 0, s[14:15]
	v_lshl_add_u64 v[178:179], v[178:179], 0, s[96:97]
	v_lshl_add_u64 v[180:181], v[180:181], 0, s[96:97]
; #define LAS __attribute__((address_space(3)))
; template <int DQK, int DV, int FLAGS, int qp, int kp, int vts, int op> ...
;     ...
;             __builtin_amdgcn_sched_barrier(0);
; #pragma unroll
;             for (int c = 0; c < ND0 / 2; ++c) {
;                 if (c + 1 < ND0 / 2) {
; #pragma unroll
;                     for (int i = 0; i < 2; ++i) { kf[(c + 1) & 1][2 * i] = *(const LAS bf16x8*)(kb + (2 * c + 2 + i) * 32); kf[(c + 1) & 1][2 * i + 1] = *(const LAS bf16x8*)(kb + 32 * KROW + (2 * c + 2 + i) * 32); }
;                 }
; #pragma unroll
;                 for (int i = 0; i < 2; ++i) {
;                     p0 = __builtin_amdgcn_mfma_f32_32x32x16_bf16(kf[c & 1][2 * i], qr[2 * c + i], p0, 0, 0, 0);
;                     p1 = __builtin_amdgcn_mfma_f32_32x32x16_bf16(kf[c & 1][2 * i + 1], qr[2 * c + i], p1, 0, 0, 0);
;                 }
;                 __builtin_amdgcn_sched_barrier(0);
;             }
;     ...
;             f32x2 rs2 = {0.f, 0.f};
; #pragma unroll
;             for (int r = 0; r < 16; ++r) { p0[r] = __builtin_amdgcn_exp2f(p0[r]); p1[r] = __builtin_amdgcn_exp2f(p1[r]); }
; #pragma unroll
;             for (int r = 0; r < 16; r += 2) { rs2 += (f32x2){p0[r], p0[r + 1]}; rs2 += (f32x2){p1[r], p1[r + 1]}; }
;             l += rs2.x + rs2.y;
;             bf16x8 pf[4];
;             pf[0] = pack_bf16x8(p0, 0); pf[1] = pack_bf16x8(p0, 8); pf[2] = pack_bf16x8(p1, 0); pf[3] = pack_bf16x8(p1, 8);
;             __builtin_amdgcn_sched_barrier(0);
; #pragma unroll
;             for (int d = 0; d < NDB; ++d) {
;                 if (d + 1 < NDB) {
; #pragma unroll
;                     for (int ks = 0; ks < 4; ++ks) vf[(d + 1) & 1][ks] = *(const LAS bf16x8*)(vb + (d + 1) * 32 * VROW + ks * 32);
;                 }
; #pragma unroll
;                 for (int ks = 0; ks < 4; ++ks) o[d] = __builtin_amdgcn_mfma_f32_32x32x16_bf16(vf[d & 1][ks], pf[ks], o[d], 0, 0, 0);
;                 __builtin_amdgcn_sched_barrier(0);
;             }
.Lr_nols_s0:
	s_waitcnt lgkmcnt(8)
	v_mfma_f32_16x16x32_bf16 v[214:217], v[96:99], v[2:5], v[48:51]
	v_mfma_f32_16x16x32_bf16 v[230:233], v[96:99], v[128:131], v[52:55]
	v_exp_f32_e32 v72, v72
	v_exp_f32_e32 v73, v73
	v_add_f32_e32 v208, v86, v208
	v_add_f32_e32 v209, v87, v209
	v_mfma_f32_16x16x32_bf16 v[218:221], v[100:103], v[2:5], v[48:51]
	v_mfma_f32_16x16x32_bf16 v[234:237], v[100:103], v[128:131], v[52:55]
	v_exp_f32_e32 v88, v88
	v_exp_f32_e32 v89, v89
	v_add_f32_e32 v204, v72, v204
	v_add_f32_e32 v205, v73, v205
	v_mfma_f32_16x16x32_bf16 v[222:225], v[104:107], v[2:5], v[48:51]
	v_mfma_f32_16x16x32_bf16 v[238:241], v[104:107], v[128:131], v[52:55]
	v_exp_f32_e32 v74, v74
	v_exp_f32_e32 v75, v75
	v_add_f32_e32 v208, v88, v208
	v_add_f32_e32 v209, v89, v209
	v_mfma_f32_16x16x32_bf16 v[226:229], v[108:111], v[2:5], v[48:51]
	v_mfma_f32_16x16x32_bf16 v[242:245], v[108:111], v[128:131], v[52:55]
	v_exp_f32_e32 v90, v90
	v_exp_f32_e32 v91, v91
	v_add_f32_e32 v204, v74, v204
	v_add_f32_e32 v205, v75, v205
	ds_read_b128 v[96:99], v206 offset:128
	ds_read_b128 v[100:103], v206 offset:960
	ds_read_b128 v[104:107], v206 offset:6784
	ds_read_b128 v[108:111], v206 offset:7616
	s_waitcnt lgkmcnt(8)
	v_mfma_f32_16x16x32_bf16 v[214:217], v[112:115], v[6:9], v[214:217]
	v_mfma_f32_16x16x32_bf16 v[230:233], v[112:115], v[132:135], v[230:233]
	v_exp_f32_e32 v76, v76
	v_exp_f32_e32 v77, v77
	v_add_f32_e32 v208, v90, v208
	v_add_f32_e32 v209, v91, v209
	v_mfma_f32_16x16x32_bf16 v[218:221], v[116:119], v[6:9], v[218:221]
	v_mfma_f32_16x16x32_bf16 v[234:237], v[116:119], v[132:135], v[234:237]
	v_exp_f32_e32 v92, v92
	v_exp_f32_e32 v93, v93
	v_add_f32_e32 v204, v76, v204
	v_add_f32_e32 v205, v77, v205
	v_mfma_f32_16x16x32_bf16 v[222:225], v[120:123], v[6:9], v[222:225]
	v_mfma_f32_16x16x32_bf16 v[238:241], v[120:123], v[132:135], v[238:241]
	v_exp_f32_e32 v78, v78
	v_exp_f32_e32 v79, v79
	v_add_f32_e32 v208, v92, v208
	v_add_f32_e32 v209, v93, v209
	v_mfma_f32_16x16x32_bf16 v[226:229], v[124:127], v[6:9], v[226:229]
	v_mfma_f32_16x16x32_bf16 v[242:245], v[124:127], v[132:135], v[242:245]
	v_exp_f32_e32 v94, v94
	v_exp_f32_e32 v95, v95
	v_add_f32_e32 v204, v78, v204
	v_add_f32_e32 v205, v79, v205
	ds_read_b128 v[188:191], v207 offset:13376
	ds_read_b128 v[192:195], v207 offset:15680
	ds_read_b128 v[196:199], v207 offset:17984
	ds_read_b128 v[200:203], v207 offset:20288
	s_waitcnt lgkmcnt(4)
	v_mfma_f32_16x16x32_bf16 v[214:217], v[96:99], v[10:13], v[214:217]
	v_mfma_f32_16x16x32_bf16 v[230:233], v[96:99], v[136:139], v[230:233]
	s_nop 0
	v_add_f32_e32 v208, v94, v208
	v_add_f32_e32 v209, v95, v209
	v_cvt_pk_bf16_f32 v64, v64, v65
	v_cvt_pk_bf16_f32 v65, v66, v67
	v_cvt_pk_bf16_f32 v66, v68, v69
	v_cvt_pk_bf16_f32 v67, v70, v71
	v_mfma_f32_16x16x32_bf16 v[218:221], v[100:103], v[10:13], v[218:221]
	v_mfma_f32_16x16x32_bf16 v[234:237], v[100:103], v[136:139], v[234:237]
	v_cvt_pk_bf16_f32 v68, v72, v73
	v_cvt_pk_bf16_f32 v69, v74, v75
	v_cvt_pk_bf16_f32 v70, v76, v77
	v_cvt_pk_bf16_f32 v71, v78, v79
	v_cvt_pk_bf16_f32 v80, v80, v81
	v_cvt_pk_bf16_f32 v81, v82, v83
	v_mfma_f32_16x16x32_bf16 v[222:225], v[104:107], v[10:13], v[222:225]
	v_mfma_f32_16x16x32_bf16 v[238:241], v[104:107], v[136:139], v[238:241]
	v_cvt_pk_bf16_f32 v82, v84, v85
	v_cvt_pk_bf16_f32 v83, v86, v87
	v_cvt_pk_bf16_f32 v84, v88, v89
	v_cvt_pk_bf16_f32 v85, v90, v91
	v_cvt_pk_bf16_f32 v86, v92, v93
	v_cvt_pk_bf16_f32 v87, v94, v95
	v_mfma_f32_16x16x32_bf16 v[226:229], v[108:111], v[10:13], v[226:229]
	v_mfma_f32_16x16x32_bf16 v[242:245], v[108:111], v[136:139], v[242:245]
	v_add_f32_e32 v210, v204, v205
	v_add_f32_e32 v211, v208, v209
	v_add_f32_e32 v175, v175, v210
	v_add_f32_e32 v249, v249, v211
	s_branch .Lr_tailb0

; template <int DQK, int DV, int FLAGS, int qp, int kp, int vts, int op> ...
;     ...
;             f32x2 rs2 = {0.f, 0.f};
; #pragma unroll
;             for (int r = 0; r < 16; ++r) { p0[r] = __builtin_amdgcn_exp2f(p0[r]); p1[r] = __builtin_amdgcn_exp2f(p1[r]); }
; #pragma unroll
;             for (int r = 0; r < 16; r += 2) { rs2 += (f32x2){p0[r], p0[r + 1]}; rs2 += (f32x2){p1[r], p1[r + 1]}; }
;             l += rs2.x + rs2.y;
;             bf16x8 pf[4];
;             pf[0] = pack_bf16x8(p0, 0); pf[1] = pack_bf16x8(p0, 8); pf[2] = pack_bf16x8(p1, 0); pf[3] = pack_bf16x8(p1, 8);
.Lr_notfirst_p0:
	v_exp_f32_e32 v64, v64
	v_exp_f32_e32 v65, v65
	v_exp_f32_e32 v80, v80
	v_exp_f32_e32 v81, v81
	v_mov_b32_e32 v204, v64
	v_mov_b32_e32 v205, v65
	v_exp_f32_e32 v66, v66
	v_exp_f32_e32 v67, v67
	v_mov_b32_e32 v208, v80
	v_mov_b32_e32 v209, v81
	v_exp_f32_e32 v82, v82
	v_exp_f32_e32 v83, v83
	v_add_f32_e32 v204, v66, v204
	v_add_f32_e32 v205, v67, v205
	v_exp_f32_e32 v68, v68
	v_exp_f32_e32 v69, v69
	v_add_f32_e32 v208, v82, v208
	v_add_f32_e32 v209, v83, v209
	v_exp_f32_e32 v84, v84
	v_exp_f32_e32 v85, v85
	v_add_f32_e32 v204, v68, v204
	v_add_f32_e32 v205, v69, v205
	v_exp_f32_e32 v70, v70
	v_exp_f32_e32 v71, v71
	v_add_f32_e32 v208, v84, v208
	v_add_f32_e32 v209, v85, v209
	v_exp_f32_e32 v86, v86
	v_exp_f32_e32 v87, v87
	v_add_f32_e32 v204, v70, v204
	v_add_f32_e32 v205, v71, v205
	v_exp_f32_e32 v72, v72
	v_exp_f32_e32 v73, v73
	v_add_f32_e32 v208, v86, v208
	v_add_f32_e32 v209, v87, v209
	v_exp_f32_e32 v88, v88
	v_exp_f32_e32 v89, v89
	v_add_f32_e32 v204, v72, v204
	v_add_f32_e32 v205, v73, v205
	v_exp_f32_e32 v74, v74
	v_exp_f32_e32 v75, v75
	v_add_f32_e32 v208, v88, v208
	v_add_f32_e32 v209, v89, v209
	v_exp_f32_e32 v90, v90
	v_exp_f32_e32 v91, v91
	v_add_f32_e32 v204, v74, v204
	v_add_f32_e32 v205, v75, v205
	v_exp_f32_e32 v76, v76
	v_exp_f32_e32 v77, v77
	v_add_f32_e32 v208, v90, v208
	v_add_f32_e32 v209, v91, v209
	v_exp_f32_e32 v92, v92
	v_exp_f32_e32 v93, v93
	v_add_f32_e32 v204, v76, v204
	v_add_f32_e32 v205, v77, v205
	v_exp_f32_e32 v78, v78
	v_exp_f32_e32 v79, v79
	v_add_f32_e32 v208, v92, v208
	v_add_f32_e32 v209, v93, v209
	v_exp_f32_e32 v94, v94
	v_exp_f32_e32 v95, v95
	v_add_f32_e32 v204, v78, v204
	v_add_f32_e32 v205, v79, v205
	s_nop 0
	v_add_f32_e32 v208, v94, v208
	v_add_f32_e32 v209, v95, v209
	v_cvt_pk_bf16_f32 v64, v64, v65
	v_cvt_pk_bf16_f32 v65, v66, v67
	v_cvt_pk_bf16_f32 v66, v68, v69
	v_cvt_pk_bf16_f32 v67, v70, v71
	v_cvt_pk_bf16_f32 v68, v72, v73
	v_cvt_pk_bf16_f32 v69, v74, v75
	v_cvt_pk_bf16_f32 v70, v76, v77
	v_cvt_pk_bf16_f32 v71, v78, v79
	v_cvt_pk_bf16_f32 v80, v80, v81
	v_cvt_pk_bf16_f32 v81, v82, v83
	v_cvt_pk_bf16_f32 v82, v84, v85
	v_cvt_pk_bf16_f32 v83, v86, v87
	v_cvt_pk_bf16_f32 v84, v88, v89
	v_cvt_pk_bf16_f32 v85, v90, v91
	v_cvt_pk_bf16_f32 v86, v92, v93
	v_cvt_pk_bf16_f32 v87, v94, v95
	v_add_f32_e32 v210, v204, v205
	v_add_f32_e32 v211, v208, v209
	v_add_f32_e32 v175, v175, v210
	v_add_f32_e32 v249, v249, v211

; #define LAS __attribute__((address_space(3)))
; template <int DQK, int DV, int FLAGS, int qp, int kp, int vts, int op> ...
;     ...
;             __builtin_amdgcn_sched_barrier(0);
; #pragma unroll
;             for (int c = 0; c < ND0 / 2; ++c) {
;                 if (c + 1 < ND0 / 2) {
; #pragma unroll
;                     for (int i = 0; i < 2; ++i) { kf[(c + 1) & 1][2 * i] = *(const LAS bf16x8*)(kb + (2 * c + 2 + i) * 32); kf[(c + 1) & 1][2 * i + 1] = *(const LAS bf16x8*)(kb + 32 * KROW + (2 * c + 2 + i) * 32); }
;                 }
; #pragma unroll
;                 for (int i = 0; i < 2; ++i) {
;                     p0 = __builtin_amdgcn_mfma_f32_32x32x16_bf16(kf[c & 1][2 * i], qr[2 * c + i], p0, 0, 0, 0);
;                     p1 = __builtin_amdgcn_mfma_f32_32x32x16_bf16(kf[c & 1][2 * i + 1], qr[2 * c + i], p1, 0, 0, 0);
;                 }
;                 __builtin_amdgcn_sched_barrier(0);
;             }
;     ...
;             f32x2 rs2 = {0.f, 0.f};
; #pragma unroll
;             for (int r = 0; r < 16; ++r) { p0[r] = __builtin_amdgcn_exp2f(p0[r]); p1[r] = __builtin_amdgcn_exp2f(p1[r]); }
; #pragma unroll
;             for (int r = 0; r < 16; r += 2) { rs2 += (f32x2){p0[r], p0[r + 1]}; rs2 += (f32x2){p1[r], p1[r + 1]}; }
;             l += rs2.x + rs2.y;
;             bf16x8 pf[4];
;             pf[0] = pack_bf16x8(p0, 0); pf[1] = pack_bf16x8(p0, 8); pf[2] = pack_bf16x8(p1, 0); pf[3] = pack_bf16x8(p1, 8);
;             __builtin_amdgcn_sched_barrier(0);
; #pragma unroll
;             for (int d = 0; d < NDB; ++d) {
;                 if (d + 1 < NDB) {
; #pragma unroll
;                     for (int ks = 0; ks < 4; ++ks) vf[(d + 1) & 1][ks] = *(const LAS bf16x8*)(vb + (d + 1) * 32 * VROW + ks * 32);
;                 }
; #pragma unroll
;                 for (int ks = 0; ks < 4; ++ks) o[d] = __builtin_amdgcn_mfma_f32_32x32x16_bf16(vf[d & 1][ks], pf[ks], o[d], 0, 0, 0);
;                 __builtin_amdgcn_sched_barrier(0);
;             }
;         }
;         if (skip && more) ATT_GLOAD((FLAGS & AF_REV) ? t - 1 : t + 1);
;         if (more) ATT_LSTORE(cur ^ 1);
;         __syncthreads();
.Lr_nols_p0:
.Lr_tailb0:
	s_add_i32 s3, s3, 1
	s_cmp_ge_i32 s3, s2
	s_cbranch_scc1 .Lr_flush1
	s_waitcnt lgkmcnt(0)
	s_barrier
.Lr_top1:
	s_cmp_eq_u32 s3, 0
	s_cbranch_scc1 .Lr_gen1
	s_add_i32 s13, s3, 1
	s_cmp_ge_i32 s13, s20
	s_cbranch_scc1 .Lr_gen1
	s_add_i32 s12, s3, 1
	s_and_b32 s12, s12, 3
	s_mulk_i32 s12, 0x5800
	v_add_u32_e32 v206, s12, v246
	ds_read_b128 v[96:99], v206 offset:0
	ds_read_b128 v[100:103], v206 offset:832
	ds_read_b128 v[104:107], v206 offset:6656
	ds_read_b128 v[108:111], v206 offset:7488
	ds_read_b128 v[112:115], v206 offset:64
	ds_read_b128 v[116:119], v206 offset:896
	ds_read_b128 v[120:123], v206 offset:6720
	ds_read_b128 v[124:127], v206 offset:7552
	s_and_b32 s16, s3, 3
	s_mulk_i32 s16, 0x5800
	v_add_u32_e32 v207, s16, v247
	v_mfma_f32_16x16x32_bf16 v[32:35], v[152:155], v[64:67], v[32:35]
	v_mfma_f32_16x16x32_bf16 v[16:19], v[152:155], v[80:83], v[16:19]
	v_exp_f32_e32 v214, v214
	v_exp_f32_e32 v215, v215
	v_mfma_f32_16x16x32_bf16 v[36:39], v[156:159], v[64:67], v[36:39]
	v_mfma_f32_16x16x32_bf16 v[20:23], v[156:159], v[80:83], v[20:23]
	v_exp_f32_e32 v230, v230
	v_exp_f32_e32 v231, v231
	v_mov_b32_e32 v204, v214
	v_mov_b32_e32 v205, v215
	v_mfma_f32_16x16x32_bf16 v[40:43], v[160:163], v[64:67], v[40:43]
	v_mfma_f32_16x16x32_bf16 v[24:27], v[160:163], v[80:83], v[24:27]
	v_exp_f32_e32 v216, v216
	v_exp_f32_e32 v217, v217
	v_mov_b32_e32 v208, v230
	v_mov_b32_e32 v209, v231
	v_mfma_f32_16x16x32_bf16 v[44:47], v[164:167], v[64:67], v[44:47]
	v_mfma_f32_16x16x32_bf16 v[28:31], v[164:167], v[80:83], v[28:31]
	v_exp_f32_e32 v232, v232
	v_exp_f32_e32 v233, v233
	v_add_f32_e32 v204, v216, v204
	v_add_f32_e32 v205, v217, v205
	ds_read_b128 v[152:155], v207 offset:13312
	ds_read_b128 v[156:159], v207 offset:15616
	ds_read_b128 v[160:163], v207 offset:17920
	ds_read_b128 v[164:167], v207 offset:20224
	v_mfma_f32_16x16x32_bf16 v[32:35], v[188:191], v[68:71], v[32:35]
	v_mfma_f32_16x16x32_bf16 v[16:19], v[188:191], v[84:87], v[16:19]
	v_exp_f32_e32 v218, v218
	v_exp_f32_e32 v219, v219
	v_add_f32_e32 v208, v232, v208
	v_add_f32_e32 v209, v233, v209
	v_mfma_f32_16x16x32_bf16 v[36:39], v[192:195], v[68:71], v[36:39]
	v_mfma_f32_16x16x32_bf16 v[20:23], v[192:195], v[84:87], v[20:23]
	v_exp_f32_e32 v234, v234
	v_exp_f32_e32 v235, v235
	v_add_f32_e32 v204, v218, v204
	v_add_f32_e32 v205, v219, v205
	v_mfma_f32_16x16x32_bf16 v[40:43], v[196:199], v[68:71], v[40:43]
	v_mfma_f32_16x16x32_bf16 v[24:27], v[196:199], v[84:87], v[24:27]
	v_exp_f32_e32 v220, v220
	v_exp_f32_e32 v221, v221
	v_add_f32_e32 v208, v234, v208
	v_add_f32_e32 v209, v235, v209
	v_mfma_f32_16x16x32_bf16 v[44:47], v[200:203], v[68:71], v[44:47]
	v_mfma_f32_16x16x32_bf16 v[28:31], v[200:203], v[84:87], v[28:31]
	v_exp_f32_e32 v236, v236
	v_exp_f32_e32 v237, v237
	v_add_f32_e32 v204, v220, v204
	v_add_f32_e32 v205, v221, v205
	s_add_i32 s12, s3, 2
	s_cmp_ge_i32 s12, s2
	s_cbranch_scc1 .Lr_nols_s1
	s_and_b32 s16, s12, 3
	s_mulk_i32 s16, 0x5800
	s_waitcnt vmcnt(0)
	v_add_u32_e32 v56, s16, v14
	v_add_u32_e32 v57, s16, v174
	v_add_u32_e32 v58, s16, v172
	ds_write_b128 v56, v[140:143]
	ds_write_b128 v57, v[148:151] offset:13312
	s_and_saveexec_b64 s[14:15], s[10:11]
	ds_write_b128 v58, v[144:147]
	s_or_b64 exec, exec, s[14:15]
	s_add_i32 s12, s3, 3
	s_cmp_ge_i32 s12, s2
	s_cbranch_scc1 .Lr_nols_s1
	s_and_saveexec_b64 s[14:15], s[10:11]
	global_load_dwordx4 v[144:147], v[180:181], off
	s_or_b64 exec, exec, s[14:15]
	global_load_dwordx4 v[140:143], v[178:179], off
	global_load_dwordx4 v[148:151], v[176:177], off
	s_mov_b64 s[14:15], 0x80
	v_lshl_add_u64 v[176:177], v[176:177], 0, s[14:15]
	v_lshl_add_u64 v[178:179], v[178:179], 0, s[96:97]
	v_lshl_add_u64 v[180:181], v[180:181], 0, s[96:97]
; #define LAS __attribute__((address_space(3)))
; template <int DQK, int DV, int FLAGS, int qp, int kp, int vts, int op> ...
;     ...
;             __builtin_amdgcn_sched_barrier(0);
; #pragma unroll
;             for (int c = 0; c < ND0 / 2; ++c) {
;                 if (c + 1 < ND0 / 2) {
; #pragma unroll
;                     for (int i = 0; i < 2; ++i) { kf[(c + 1) & 1][2 * i] = *(const LAS bf16x8*)(kb + (2 * c + 2 + i) * 32); kf[(c + 1) & 1][2 * i + 1] = *(const LAS bf16x8*)(kb + 32 * KROW + (2 * c + 2 + i) * 32); }
;                 }
; #pragma unroll
;                 for (int i = 0; i < 2; ++i) {
;                     p0 = __builtin_amdgcn_mfma_f32_32x32x16_bf16(kf[c & 1][2 * i], qr[2 * c + i], p0, 0, 0, 0);
;                     p1 = __builtin_amdgcn_mfma_f32_32x32x16_bf16(kf[c & 1][2 * i + 1], qr[2 * c + i], p1, 0, 0, 0);
;                 }
;                 __builtin_amdgcn_sched_barrier(0);
;             }
;     ...
;             f32x2 rs2 = {0.f, 0.f};
; #pragma unroll
;             for (int r = 0; r < 16; ++r) { p0[r] = __builtin_amdgcn_exp2f(p0[r]); p1[r] = __builtin_amdgcn_exp2f(p1[r]); }
; #pragma unroll
;             for (int r = 0; r < 16; r += 2) { rs2 += (f32x2){p0[r], p0[r + 1]}; rs2 += (f32x2){p1[r], p1[r + 1]}; }
;             l += rs2.x + rs2.y;
;             bf16x8 pf[4];
;             pf[0] = pack_bf16x8(p0, 0); pf[1] = pack_bf16x8(p0, 8); pf[2] = pack_bf16x8(p1, 0); pf[3] = pack_bf16x8(p1, 8);
;             __builtin_amdgcn_sched_barrier(0);
; #pragma unroll
;             for (int d = 0; d < NDB; ++d) {
;                 if (d + 1 < NDB) {
; #pragma unroll
;                     for (int ks = 0; ks < 4; ++ks) vf[(d + 1) & 1][ks] = *(const LAS bf16x8*)(vb + (d + 1) * 32 * VROW + ks * 32);
;                 }
; #pragma unroll
;                 for (int ks = 0; ks < 4; ++ks) o[d] = __builtin_amdgcn_mfma_f32_32x32x16_bf16(vf[d & 1][ks], pf[ks], o[d], 0, 0, 0);
;                 __builtin_amdgcn_sched_barrier(0);
;             }
.Lr_nols_s1:
	s_waitcnt lgkmcnt(8)
	v_mfma_f32_16x16x32_bf16 v[64:67], v[96:99], v[2:5], v[48:51]
	v_mfma_f32_16x16x32_bf16 v[80:83], v[96:99], v[128:131], v[52:55]
	v_exp_f32_e32 v222, v222
	v_exp_f32_e32 v223, v223
	v_add_f32_e32 v208, v236, v208
	v_add_f32_e32 v209, v237, v209
	v_mfma_f32_16x16x32_bf16 v[68:71], v[100:103], v[2:5], v[48:51]
	v_mfma_f32_16x16x32_bf16 v[84:87], v[100:103], v[128:131], v[52:55]
	v_exp_f32_e32 v238, v238
	v_exp_f32_e32 v239, v239
	v_add_f32_e32 v204, v222, v204
	v_add_f32_e32 v205, v223, v205
	v_mfma_f32_16x16x32_bf16 v[72:75], v[104:107], v[2:5], v[48:51]
	v_mfma_f32_16x16x32_bf16 v[88:91], v[104:107], v[128:131], v[52:55]
	v_exp_f32_e32 v224, v224
	v_exp_f32_e32 v225, v225
	v_add_f32_e32 v208, v238, v208
	v_add_f32_e32 v209, v239, v209
	v_mfma_f32_16x16x32_bf16 v[76:79], v[108:111], v[2:5], v[48:51]
	v_mfma_f32_16x16x32_bf16 v[92:95], v[108:111], v[128:131], v[52:55]
	v_exp_f32_e32 v240, v240
	v_exp_f32_e32 v241, v241
	v_add_f32_e32 v204, v224, v204
	v_add_f32_e32 v205, v225, v205
	ds_read_b128 v[96:99], v206 offset:128
	ds_read_b128 v[100:103], v206 offset:960
	ds_read_b128 v[104:107], v206 offset:6784
	ds_read_b128 v[108:111], v206 offset:7616
	s_waitcnt lgkmcnt(8)
	v_mfma_f32_16x16x32_bf16 v[64:67], v[112:115], v[6:9], v[64:67]
	v_mfma_f32_16x16x32_bf16 v[80:83], v[112:115], v[132:135], v[80:83]
	v_exp_f32_e32 v226, v226
	v_exp_f32_e32 v227, v227
	v_add_f32_e32 v208, v240, v208
	v_add_f32_e32 v209, v241, v209
	v_mfma_f32_16x16x32_bf16 v[68:71], v[116:119], v[6:9], v[68:71]
	v_mfma_f32_16x16x32_bf16 v[84:87], v[116:119], v[132:135], v[84:87]
	v_exp_f32_e32 v242, v242
	v_exp_f32_e32 v243, v243
	v_add_f32_e32 v204, v226, v204
	v_add_f32_e32 v205, v227, v205
	v_mfma_f32_16x16x32_bf16 v[72:75], v[120:123], v[6:9], v[72:75]
	v_mfma_f32_16x16x32_bf16 v[88:91], v[120:123], v[132:135], v[88:91]
	v_exp_f32_e32 v228, v228
	v_exp_f32_e32 v229, v229
	v_add_f32_e32 v208, v242, v208
	v_add_f32_e32 v209, v243, v209
	v_mfma_f32_16x16x32_bf16 v[76:79], v[124:127], v[6:9], v[76:79]
	v_mfma_f32_16x16x32_bf16 v[92:95], v[124:127], v[132:135], v[92:95]
	v_exp_f32_e32 v244, v244
	v_exp_f32_e32 v245, v245
	v_add_f32_e32 v204, v228, v204
	v_add_f32_e32 v205, v229, v205
	ds_read_b128 v[188:191], v207 offset:13376
	ds_read_b128 v[192:195], v207 offset:15680
	ds_read_b128 v[196:199], v207 offset:17984
	ds_read_b128 v[200:203], v207 offset:20288
	s_waitcnt lgkmcnt(4)
	v_mfma_f32_16x16x32_bf16 v[64:67], v[96:99], v[10:13], v[64:67]
	v_mfma_f32_16x16x32_bf16 v[80:83], v[96:99], v[136:139], v[80:83]
	s_nop 0
	v_add_f32_e32 v208, v244, v208
	v_add_f32_e32 v209, v245, v209
	v_cvt_pk_bf16_f32 v214, v214, v215
	v_cvt_pk_bf16_f32 v215, v216, v217
	v_cvt_pk_bf16_f32 v216, v218, v219
	v_cvt_pk_bf16_f32 v217, v220, v221
	v_mfma_f32_16x16x32_bf16 v[68:71], v[100:103], v[10:13], v[68:71]
	v_mfma_f32_16x16x32_bf16 v[84:87], v[100:103], v[136:139], v[84:87]
	v_cvt_pk_bf16_f32 v218, v222, v223
	v_cvt_pk_bf16_f32 v219, v224, v225
	v_cvt_pk_bf16_f32 v220, v226, v227
	v_cvt_pk_bf16_f32 v221, v228, v229
	v_cvt_pk_bf16_f32 v230, v230, v231
	v_cvt_pk_bf16_f32 v231, v232, v233
	v_mfma_f32_16x16x32_bf16 v[72:75], v[104:107], v[10:13], v[72:75]
	v_mfma_f32_16x16x32_bf16 v[88:91], v[104:107], v[136:139], v[88:91]
	v_cvt_pk_bf16_f32 v232, v234, v235
	v_cvt_pk_bf16_f32 v233, v236, v237
	v_cvt_pk_bf16_f32 v234, v238, v239
	v_cvt_pk_bf16_f32 v235, v240, v241
	v_cvt_pk_bf16_f32 v236, v242, v243
	v_cvt_pk_bf16_f32 v237, v244, v245
	v_mfma_f32_16x16x32_bf16 v[76:79], v[108:111], v[10:13], v[76:79]
	v_mfma_f32_16x16x32_bf16 v[92:95], v[108:111], v[136:139], v[92:95]
	v_add_f32_e32 v210, v204, v205
	v_add_f32_e32 v211, v208, v209
	v_add_f32_e32 v175, v175, v210
	v_add_f32_e32 v249, v249, v211
	s_branch .Lr_tailb1

; template <int DQK, int DV, int FLAGS, int qp, int kp, int vts, int op> ...
;     ...
;             f32x2 rs2 = {0.f, 0.f};
; #pragma unroll
;             for (int r = 0; r < 16; ++r) { p0[r] = __builtin_amdgcn_exp2f(p0[r]); p1[r] = __builtin_amdgcn_exp2f(p1[r]); }
; #pragma unroll
;             for (int r = 0; r < 16; r += 2) { rs2 += (f32x2){p0[r], p0[r + 1]}; rs2 += (f32x2){p1[r], p1[r + 1]}; }
;             l += rs2.x + rs2.y;
;             bf16x8 pf[4];
;             pf[0] = pack_bf16x8(p0, 0); pf[1] = pack_bf16x8(p0, 8); pf[2] = pack_bf16x8(p1, 0); pf[3] = pack_bf16x8(p1, 8);
.Lr_notfirst_p1:
	v_exp_f32_e32 v214, v214
	v_exp_f32_e32 v215, v215
	v_exp_f32_e32 v230, v230
	v_exp_f32_e32 v231, v231
	v_mov_b32_e32 v204, v214
	v_mov_b32_e32 v205, v215
	v_exp_f32_e32 v216, v216
	v_exp_f32_e32 v217, v217
	v_mov_b32_e32 v208, v230
	v_mov_b32_e32 v209, v231
	v_exp_f32_e32 v232, v232
	v_exp_f32_e32 v233, v233
	v_add_f32_e32 v204, v216, v204
	v_add_f32_e32 v205, v217, v205
	v_exp_f32_e32 v218, v218
	v_exp_f32_e32 v219, v219
	v_add_f32_e32 v208, v232, v208
	v_add_f32_e32 v209, v233, v209
	v_exp_f32_e32 v234, v234
	v_exp_f32_e32 v235, v235
	v_add_f32_e32 v204, v218, v204
	v_add_f32_e32 v205, v219, v205
	v_exp_f32_e32 v220, v220
	v_exp_f32_e32 v221, v221
	v_add_f32_e32 v208, v234, v208
	v_add_f32_e32 v209, v235, v209
	v_exp_f32_e32 v236, v236
	v_exp_f32_e32 v237, v237
	v_add_f32_e32 v204, v220, v204
	v_add_f32_e32 v205, v221, v205
	v_exp_f32_e32 v222, v222
	v_exp_f32_e32 v223, v223
	v_add_f32_e32 v208, v236, v208
	v_add_f32_e32 v209, v237, v209
	v_exp_f32_e32 v238, v238
	v_exp_f32_e32 v239, v239
	v_add_f32_e32 v204, v222, v204
	v_add_f32_e32 v205, v223, v205
	v_exp_f32_e32 v224, v224
	v_exp_f32_e32 v225, v225
	v_add_f32_e32 v208, v238, v208
	v_add_f32_e32 v209, v239, v209
	v_exp_f32_e32 v240, v240
	v_exp_f32_e32 v241, v241
	v_add_f32_e32 v204, v224, v204
	v_add_f32_e32 v205, v225, v205
	v_exp_f32_e32 v226, v226
	v_exp_f32_e32 v227, v227
	v_add_f32_e32 v208, v240, v208
	v_add_f32_e32 v209, v241, v209
	v_exp_f32_e32 v242, v242
	v_exp_f32_e32 v243, v243
	v_add_f32_e32 v204, v226, v204
	v_add_f32_e32 v205, v227, v205
	v_exp_f32_e32 v228, v228
	v_exp_f32_e32 v229, v229
	v_add_f32_e32 v208, v242, v208
	v_add_f32_e32 v209, v243, v209
	v_exp_f32_e32 v244, v244
	v_exp_f32_e32 v245, v245
	v_add_f32_e32 v204, v228, v204
	v_add_f32_e32 v205, v229, v205
	s_nop 0
	v_add_f32_e32 v208, v244, v208
	v_add_f32_e32 v209, v245, v209
	v_cvt_pk_bf16_f32 v214, v214, v215
	v_cvt_pk_bf16_f32 v215, v216, v217
	v_cvt_pk_bf16_f32 v216, v218, v219
	v_cvt_pk_bf16_f32 v217, v220, v221
	v_cvt_pk_bf16_f32 v218, v222, v223
	v_cvt_pk_bf16_f32 v219, v224, v225
	v_cvt_pk_bf16_f32 v220, v226, v227
	v_cvt_pk_bf16_f32 v221, v228, v229
	v_cvt_pk_bf16_f32 v230, v230, v231
	v_cvt_pk_bf16_f32 v231, v232, v233
	v_cvt_pk_bf16_f32 v232, v234, v235
	v_cvt_pk_bf16_f32 v233, v236, v237
	v_cvt_pk_bf16_f32 v234, v238, v239
	v_cvt_pk_bf16_f32 v235, v240, v241
	v_cvt_pk_bf16_f32 v236, v242, v243
	v_cvt_pk_bf16_f32 v237, v244, v245
	v_add_f32_e32 v210, v204, v205
	v_add_f32_e32 v211, v208, v209
	v_add_f32_e32 v175, v175, v210
	v_add_f32_e32 v249, v249, v211

; #define ATT_LSTORE(buf) do { LAS unsigned char* b_ = lds + (buf) * BUF; \
;         _Pragma("unroll") for (int i = 0; i < KPT; ++i) { if (KCH % NTHREADS == 0 || tid + i * NTHREADS < KCH) *(LAS u32x4*)(b_ + klo[i]) = kreg[i]; } \
;         _Pragma("unroll") for (int i = 0; i < VPT; ++i) *(LAS u32x4*)(b_ + vlo[i]) = vreg[i]; } while (0)
; template <int DQK, int DV, int FLAGS, int qp, int kp, int vts, int op> ...
;     ...
;         if (skip && more) ATT_GLOAD((FLAGS & AF_REV) ? t - 1 : t + 1);
;         if (more) ATT_LSTORE(cur ^ 1);
;         __syncthreads();
;     }
.Lr_nols_p1:
.Lr_tailb1:
	s_add_i32 s3, s3, 1
	s_cmp_ge_i32 s3, s2
	s_cbranch_scc1 .Lr_flush0
	s_waitcnt lgkmcnt(0)
	s_barrier
	s_branch .Lr_top0

; #define LAS __attribute__((address_space(3)))
; template <int DQK, int DV, int FLAGS, int qp, int kp, int vts, int op> ...
;     ...
;     f32x16 o[NDB];
; #pragma unroll
;     for (int d = 0; d < NDB; ++d)
; #pragma unroll
;         for (int r = 0; r < 16; ++r) o[d][r] = 0.f;
;     float m = (FLAGS & AF_ROBUST) ? -1e30f : 0.f, l = 0.f;
;     f32x16 negm;
; #pragma unroll
;     for (int r = 0; r < 16; ++r) negm[r] = 0.f;
;     u32x4 kreg[KPT], vreg[VPT];
;     unsigned kgo[KPT], vgo[VPT], klo[KPT], vlo[VPT];
; #pragma unroll
;     for (int i = 0; i < KPT; ++i) { const int c = tid + i * NTHREADS; const int row = c / KC, cc = c % KC; kgo[i] = (unsigned)(row * kp + cc * 8) * 2u; klo[i] = (unsigned)(row * KROW + cc * 16); }
; #pragma unroll
;     for (int i = 0; i < VPT; ++i) { const int c = tid + i * NTHREADS; const int d = c >> 3, cc = c & 7; vgo[i] = (unsigned)(d * vts + cc * 8) * 2u; vlo[i] = (unsigned)(KT_BYTES + d * VROW + cc * 16); }
;     ...
;     ATT_GLOAD((FLAGS & AF_REV) ? kt_hi - 1 : kt_lo); ATT_LSTORE(0);
;     __syncthreads();
;     ...
;             if (FLAGS & AF_ALIBI) { const float ab = -slope2 * (float)nrel - ((FLAGS & AF_ROBUST) ? 0.f : m);
; #pragma unroll
;                 for (int r = 0; r < 16; ++r) { const float c = (float)(16 * (r >> 3) + (r & 7)); p0[r] = __builtin_fmaf(slope2, c, ab); p1[r] = __builtin_fmaf(slope2, c + 32.f, ab); }
;             } else if (FLAGS & AF_ROBUST) {
; #pragma unroll
;                 for (int r = 0; r < 16; ++r) { p0[r] = 0.f; p1[r] = 0.f; }
;             } else { p0 = negm; p1 = negm; }
;             __builtin_amdgcn_sched_barrier(0);
; #pragma unroll
;             for (int c = 0; c < ND0 / 2; ++c) {
;                 if (c + 1 < ND0 / 2) {
; #pragma unroll
;                     for (int i = 0; i < 2; ++i) { kf[(c + 1) & 1][2 * i] = *(const LAS bf16x8*)(kb + (2 * c + 2 + i) * 32); kf[(c + 1) & 1][2 * i + 1] = *(const LAS bf16x8*)(kb + 32 * KROW + (2 * c + 2 + i) * 32); }
;                 }
; #pragma unroll
;                 for (int i = 0; i < 2; ++i) {
;                     p0 = __builtin_amdgcn_mfma_f32_32x32x16_bf16(kf[c & 1][2 * i], qr[2 * c + i], p0, 0, 0, 0);
;                     p1 = __builtin_amdgcn_mfma_f32_32x32x16_bf16(kf[c & 1][2 * i + 1], qr[2 * c + i], p1, 0, 0, 0);
;                 }
;                 __builtin_amdgcn_sched_barrier(0);
;             }
.LBB0_933:
	s_andn2_b64 vcc, exec, s[8:9]
	v_lshlrev_b32_e32 v198, 3, v17
	s_cbranch_vccnz .LBB0_923
	v_and_b32_e32 v18, 31, v15
	v_and_b32_e32 v19, 19, v15
	v_lshlrev_b32_e32 v20, 1, v15
	v_lshrrev_b32_e32 v15, 1, v15
	s_and_b32 s8, s2, 0xffffffe0
	v_readlane_b32 s12, v255, 39
	v_and_b32_e32 v20, 8, v20
	v_and_b32_e32 v15, 4, v15
	v_mov_b32_e32 v17, v1
	s_add_i32 s20, s8, s12
	v_or3_b32 v15, v19, v20, v15
	s_addk_i32 s8, 0xff40
	v_mov_b32_e32 v64, v1
	v_mov_b32_e32 v65, v1
	v_mul_u32_u24_e32 v201, 0x90, v15
	v_mul_u32_u24_e32 v203, 0x90, v18
	v_lshl_add_u64 v[206:207], s[6:7], 0, v[16:17]
	v_add_u32_e32 v15, s8, v18
	v_mov_b32_e32 v66, v1
	v_mov_b32_e32 v67, v1
	v_mov_b32_e32 v68, v1
	v_mov_b32_e32 v69, v1
	v_mov_b32_e32 v70, v1
	v_mov_b32_e32 v71, v1
	v_mov_b32_e32 v72, v1
	v_mov_b32_e32 v73, v1
	v_mov_b32_e32 v74, v1
	v_mov_b32_e32 v75, v1
	v_mov_b32_e32 v76, v1
	v_mov_b32_e32 v77, v1
	v_mov_b32_e32 v78, v1
	v_mov_b32_e32 v79, v1
	v_mov_b64_e32 v[48:49], v[64:65]
	v_mov_b64_e32 v[32:33], v[64:65]
	v_mov_b64_e32 v[16:17], v[64:65]
	v_mov_b32_e32 v197, v1
	s_or_b32 s21, s20, 31
	s_add_i32 s2, s3, 0xff
	s_addk_i32 s3, 0x100
	v_mov_b32_e32 v208, v14
	v_mov_b32_e32 v209, v14
	v_mov_b32_e32 v210, v14
	v_mov_b32_e32 v211, v14
	s_sub_i32 s34, 0xfe, s11
	v_sub_u32_e32 v205, v15, v198
	s_sub_i32 s22, 0x3fff, s10
	s_mov_b32 s23, 0
	s_mov_b64 s[36:37], 0
	v_mov_b32_e32 v222, 0
	v_mov_b64_e32 v[50:51], v[66:67]
	v_mov_b64_e32 v[52:53], v[68:69]
	v_mov_b64_e32 v[54:55], v[70:71]
	v_mov_b64_e32 v[56:57], v[72:73]
	v_mov_b64_e32 v[58:59], v[74:75]
	v_mov_b64_e32 v[60:61], v[76:77]
	v_mov_b64_e32 v[62:63], v[78:79]
	v_mov_b64_e32 v[34:35], v[66:67]
	v_mov_b64_e32 v[36:37], v[68:69]
	v_mov_b64_e32 v[38:39], v[70:71]
	v_mov_b64_e32 v[40:41], v[72:73]
	v_mov_b64_e32 v[42:43], v[74:75]
	v_mov_b64_e32 v[44:45], v[76:77]
	v_mov_b64_e32 v[46:47], v[78:79]
	v_mov_b64_e32 v[18:19], v[66:67]
	v_mov_b64_e32 v[20:21], v[68:69]
	v_mov_b64_e32 v[22:23], v[70:71]
	v_mov_b64_e32 v[24:25], v[72:73]
	v_mov_b64_e32 v[26:27], v[74:75]
	v_mov_b64_e32 v[28:29], v[76:77]
	v_mov_b64_e32 v[30:31], v[78:79]
	v_mov_b32_e32 v199, 0
	v_readlane_b32 s13, v255, 40
	s_andn2_b64 vcc, exec, s[40:41]
	s_cbranch_vccnz .Ld_fallback
	s_ashr_i32 s35, s34, 31
	s_lshl_b64 s[6:7], s[34:35], 17
	s_lshl_b64 s[10:11], s[34:35], 7
	s_add_u32 s10, s18, s10
	s_addc_u32 s11, s19, s11
	v_lshl_add_u64 v[246:247], v[206:207], 0, s[6:7]
	global_load_dwordx4 v[148:151], v[246:247], off
	v_lshl_add_u64 v[246:247], s[10:11], 0, v[0:1]
	global_load_dwordx4 v[152:155], v[246:247], off
	v_lshl_add_u64 v[246:247], s[10:11], 0, v[196:197]
	global_load_dwordx4 v[156:159], v[246:247], off
	s_add_i32 s34, s34, -1
	s_movk_i32 s13, 0x6c00
	s_waitcnt vmcnt(0)
	v_add_u32_e32 v248, s13, v204
	v_add_u32_e32 v249, s13, v200
	v_add_u32_e32 v250, s13, v202
	ds_write_b128 v248, v[148:151]
	ds_write_b128 v249, v[152:155] offset:9216
	ds_write_b128 v250, v[156:159] offset:9216
	s_ashr_i32 s35, s34, 31
	s_lshl_b64 s[6:7], s[34:35], 17
	s_lshl_b64 s[10:11], s[34:35], 7
	s_add_u32 s10, s18, s10
	s_addc_u32 s11, s19, s11
	v_lshl_add_u64 v[246:247], v[206:207], 0, s[6:7]
	global_load_dwordx4 v[148:151], v[246:247], off
	v_lshl_add_u64 v[246:247], s[10:11], 0, v[0:1]
	global_load_dwordx4 v[152:155], v[246:247], off
	v_lshl_add_u64 v[246:247], s[10:11], 0, v[196:197]
	global_load_dwordx4 v[156:159], v[246:247], off
	s_add_i32 s34, s34, -1
	s_mov_b32 s8, 0x42000000
	s_mov_b32 s9, 0x42040000
	s_sub_i32 s24, s22, s21
	s_ashr_i32 s24, s24, 6
	s_max_i32 s24, s24, 0
	s_waitcnt lgkmcnt(0)
	s_barrier
	s_cmp_lg_u32 s24, 0
	s_cbranch_scc1 .Ld_noqk0
	v_add_u32_e32 v244, v201, v194
	ds_read_b128 v[160:163], v244 offset:0
	ds_read_b128 v[164:167], v244 offset:32
	ds_read_b128 v[168:171], v244 offset:64
	ds_read_b128 v[172:175], v244 offset:96
	ds_read_b128 v[224:227], v244 offset:4608
	ds_read_b128 v[228:231], v244 offset:4640
	ds_read_b128 v[232:235], v244 offset:4672
	ds_read_b128 v[236:239], v244 offset:4704
	v_cvt_f32_i32_e32 v246, v205
	v_fma_f32 v242, -v14, v246, -v222
	v_mov_b32_e32 v80, v242
	v_add_f32_e32 v81, v14, v242
	v_fma_f32 v82, v14, s62, v242
	v_fma_f32 v83, v14, s63, v242
	v_fma_f32 v84, v14, s64, v242
	v_fma_f32 v85, v14, s65, v242
	v_fma_f32 v86, v14, s66, v242
	v_fma_f32 v87, v14, s67, v242
	v_fma_f32 v88, v14, s68, v242
	v_fma_f32 v89, v14, s69, v242
	v_fma_f32 v90, v14, s70, v242
	v_fma_f32 v91, v14, s71, v242
	v_fma_f32 v92, v14, s72, v242
	v_fma_f32 v93, v14, s73, v242
	v_fma_f32 v94, v14, s76, v242
	v_fma_f32 v95, v14, s77, v242
	v_fma_f32 v96, v14, s8, v242
	v_fma_f32 v97, v14, s9, v242
	v_fma_f32 v98, v14, s96, v242
	v_fma_f32 v99, v14, s97, v242
	v_fma_f32 v100, v14, s94, v242
	v_fma_f32 v101, v14, s95, v242
	v_fma_f32 v102, v14, s92, v242
	v_fma_f32 v103, v14, s93, v242
	v_fma_f32 v104, v14, s90, v242
	v_fma_f32 v105, v14, s91, v242
	v_fma_f32 v106, v14, s88, v242
	v_fma_f32 v107, v14, s89, v242
	v_fma_f32 v108, v14, s86, v242
	v_fma_f32 v109, v14, s87, v242
	v_fma_f32 v110, v14, s78, v242
	v_fma_f32 v111, v14, s79, v242
	s_waitcnt lgkmcnt(0)
	v_mfma_f32_32x32x16_bf16 v[80:95], v[160:163], v[2:5], v[80:95]
	v_mfma_f32_32x32x16_bf16 v[96:111], v[224:227], v[2:5], v[96:111]
	v_mfma_f32_32x32x16_bf16 v[80:95], v[164:167], v[6:9], v[80:95]
	v_mfma_f32_32x32x16_bf16 v[96:111], v[228:231], v[6:9], v[96:111]
	v_mfma_f32_32x32x16_bf16 v[80:95], v[168:171], v[10:13], v[80:95]
	v_mfma_f32_32x32x16_bf16 v[96:111], v[232:235], v[10:13], v[96:111]
	v_mfma_f32_32x32x16_bf16 v[80:95], v[172:175], v[144:147], v[80:95]
	v_mfma_f32_32x32x16_bf16 v[96:111], v[236:239], v[144:147], v[96:111]
; #define LAS __attribute__((address_space(3)))
; template <int DQK, int DV, int FLAGS, int qp, int kp, int vts, int op> ...
;     ...
;             if (FLAGS & AF_ALIBI) { const float ab = -slope2 * (float)nrel - ((FLAGS & AF_ROBUST) ? 0.f : m);
; #pragma unroll
;                 for (int r = 0; r < 16; ++r) { const float c = (float)(16 * (r >> 3) + (r & 7)); p0[r] = __builtin_fmaf(slope2, c, ab); p1[r] = __builtin_fmaf(slope2, c + 32.f, ab); }
;             } else if (FLAGS & AF_ROBUST) {
; #pragma unroll
;                 for (int r = 0; r < 16; ++r) { p0[r] = 0.f; p1[r] = 0.f; }
;             } else { p0 = negm; p1 = negm; }
;             __builtin_amdgcn_sched_barrier(0);
; #pragma unroll
;             for (int c = 0; c < ND0 / 2; ++c) {
;                 if (c + 1 < ND0 / 2) {
; #pragma unroll
;                     for (int i = 0; i < 2; ++i) { kf[(c + 1) & 1][2 * i] = *(const LAS bf16x8*)(kb + (2 * c + 2 + i) * 32); kf[(c + 1) & 1][2 * i + 1] = *(const LAS bf16x8*)(kb + 32 * KROW + (2 * c + 2 + i) * 32); }
;                 }
; #pragma unroll
;                 for (int i = 0; i < 2; ++i) {
;                     p0 = __builtin_amdgcn_mfma_f32_32x32x16_bf16(kf[c & 1][2 * i], qr[2 * c + i], p0, 0, 0, 0);
;                     p1 = __builtin_amdgcn_mfma_f32_32x32x16_bf16(kf[c & 1][2 * i + 1], qr[2 * c + i], p1, 0, 0, 0);
;                 }
;     ...
;             f32x2 rs2 = {0.f, 0.f};
; #pragma unroll
;             for (int r = 0; r < 16; ++r) { p0[r] = __builtin_amdgcn_exp2f(p0[r]); p1[r] = __builtin_amdgcn_exp2f(p1[r]); }
; #pragma unroll
;             for (int r = 0; r < 16; r += 2) { rs2 += (f32x2){p0[r], p0[r + 1]}; rs2 += (f32x2){p1[r], p1[r + 1]}; }
;             l += rs2.x + rs2.y;
;             bf16x8 pf[4];
;             pf[0] = pack_bf16x8(p0, 0); pf[1] = pack_bf16x8(p0, 8); pf[2] = pack_bf16x8(p1, 0); pf[3] = pack_bf16x8(p1, 8);
;             __builtin_amdgcn_sched_barrier(0);
; #pragma unroll
;             for (int d = 0; d < NDB; ++d) {
;                 if (d + 1 < NDB) {
; #pragma unroll
;                     for (int ks = 0; ks < 4; ++ks) vf[(d + 1) & 1][ks] = *(const LAS bf16x8*)(vb + (d + 1) * 32 * VROW + ks * 32);
;                 }
; #pragma unroll
;                 for (int ks = 0; ks < 4; ++ks) o[d] = __builtin_amdgcn_mfma_f32_32x32x16_bf16(vf[d & 1][ks], pf[ks], o[d], 0, 0, 0);
;                 __builtin_amdgcn_sched_barrier(0);
;             }
.Ld_noqk0:
.Ld_top0:
	s_cmp_le_i32 s23, s24
	s_cbranch_scc1 .Ld_gen0
	s_add_i32 s13, s23, 1
	s_cmp_ge_i32 s13, s3
	s_cbranch_scc1 .Ld_gen0
	s_add_i32 s12, s23, -1
	s_and_b32 s12, s12, 3
	s_mulk_i32 s12, 0x6c00
	v_add3_u32 v245, s12, v203, v194
	ds_read_b128 v[224:227], v245 offset:13824
	ds_read_b128 v[228:231], v245 offset:13856
	ds_read_b128 v[232:235], v245 offset:13888
	ds_read_b128 v[236:239], v245 offset:13920
	s_add_i32 s12, s23, 1
	s_and_b32 s12, s12, 3
	s_mulk_i32 s12, 0x6c00
	v_add3_u32 v244, s12, v201, v194
	s_and_b32 s12, s23, 3
	s_mulk_i32 s12, 0x6c00
	v_add3_u32 v251, s12, v203, v194
	v_mfma_f32_32x32x16_bf16 v[64:79], v[160:163], v[112:115], v[64:79]
	v_mfma_f32_32x32x16_bf16 v[64:79], v[164:167], v[116:119], v[64:79]
	v_mfma_f32_32x32x16_bf16 v[64:79], v[168:171], v[120:123], v[64:79]
	v_mfma_f32_32x32x16_bf16 v[64:79], v[172:175], v[124:127], v[64:79]
	ds_read_b128 v[160:163], v245 offset:18432
	ds_read_b128 v[164:167], v245 offset:18464
	ds_read_b128 v[168:171], v245 offset:18496
	ds_read_b128 v[172:175], v245 offset:18528
	v_exp_f32_e32 v80, v80
	v_exp_f32_e32 v81, v81
	v_exp_f32_e32 v96, v96
	v_exp_f32_e32 v97, v97
	v_mov_b32_e32 v240, v80
	v_mov_b32_e32 v241, v81
	v_exp_f32_e32 v82, v82
	v_exp_f32_e32 v83, v83
	v_add_f32_e32 v240, v96, v240
	v_add_f32_e32 v241, v97, v241
	v_exp_f32_e32 v98, v98
	v_exp_f32_e32 v99, v99
	v_add_f32_e32 v240, v82, v240
	v_add_f32_e32 v241, v83, v241
	s_waitcnt lgkmcnt(4)
	v_mfma_f32_32x32x16_bf16 v[48:63], v[224:227], v[112:115], v[48:63]
	v_mfma_f32_32x32x16_bf16 v[48:63], v[228:231], v[116:119], v[48:63]
	v_mfma_f32_32x32x16_bf16 v[48:63], v[232:235], v[120:123], v[48:63]
	v_mfma_f32_32x32x16_bf16 v[48:63], v[236:239], v[124:127], v[48:63]
	ds_read_b128 v[224:227], v245 offset:23040
	ds_read_b128 v[228:231], v245 offset:23072
	ds_read_b128 v[232:235], v245 offset:23104
	ds_read_b128 v[236:239], v245 offset:23136
	v_exp_f32_e32 v84, v84
	v_exp_f32_e32 v85, v85
	v_add_f32_e32 v240, v98, v240
	v_add_f32_e32 v241, v99, v241
	v_exp_f32_e32 v100, v100
	v_exp_f32_e32 v101, v101
	v_add_f32_e32 v240, v84, v240
	v_add_f32_e32 v241, v85, v241
	v_exp_f32_e32 v86, v86
	v_exp_f32_e32 v87, v87
	v_add_f32_e32 v240, v100, v240
	v_add_f32_e32 v241, v101, v241
	v_exp_f32_e32 v102, v102
	v_exp_f32_e32 v103, v103
	v_add_f32_e32 v240, v86, v240
	v_add_f32_e32 v241, v87, v241
	s_waitcnt lgkmcnt(4)
	v_mfma_f32_32x32x16_bf16 v[32:47], v[160:163], v[112:115], v[32:47]
	v_mfma_f32_32x32x16_bf16 v[32:47], v[164:167], v[116:119], v[32:47]
	v_mfma_f32_32x32x16_bf16 v[32:47], v[168:171], v[120:123], v[32:47]
	v_mfma_f32_32x32x16_bf16 v[32:47], v[172:175], v[124:127], v[32:47]
	ds_read_b128 v[160:163], v244 offset:0
	ds_read_b128 v[164:167], v244 offset:32
	ds_read_b128 v[168:171], v244 offset:64
	ds_read_b128 v[172:175], v244 offset:96
	v_exp_f32_e32 v88, v88
	v_exp_f32_e32 v89, v89
	v_add_f32_e32 v240, v102, v240
	v_add_f32_e32 v241, v103, v241
	v_exp_f32_e32 v104, v104
	v_exp_f32_e32 v105, v105
	v_add_f32_e32 v240, v88, v240
	v_add_f32_e32 v241, v89, v241
	v_exp_f32_e32 v90, v90
	v_exp_f32_e32 v91, v91
	v_add_f32_e32 v240, v104, v240
	v_add_f32_e32 v241, v105, v241
	v_exp_f32_e32 v106, v106
	v_exp_f32_e32 v107, v107
	v_add_f32_e32 v240, v90, v240
	v_add_f32_e32 v241, v91, v241
	s_waitcnt lgkmcnt(4)
	v_mfma_f32_32x32x16_bf16 v[16:31], v[224:227], v[112:115], v[16:31]
	v_mfma_f32_32x32x16_bf16 v[16:31], v[228:231], v[116:119], v[16:31]
	v_mfma_f32_32x32x16_bf16 v[16:31], v[232:235], v[120:123], v[16:31]
	v_mfma_f32_32x32x16_bf16 v[16:31], v[236:239], v[124:127], v[16:31]
	ds_read_b128 v[224:227], v244 offset:4608
	ds_read_b128 v[228:231], v244 offset:4640
	ds_read_b128 v[232:235], v244 offset:4672
	ds_read_b128 v[236:239], v244 offset:4704
	v_add_u32_e32 v246, 64, v205
	v_cvt_f32_i32_e32 v246, v246
	v_fma_f32 v242, -v14, v246, -v222
	v_mov_b32_e32 v112, v242
	v_add_f32_e32 v113, v14, v242
	v_fma_f32 v114, v14, s62, v242
	v_fma_f32 v115, v14, s63, v242
	v_fma_f32 v116, v14, s64, v242
	v_fma_f32 v117, v14, s65, v242
	v_fma_f32 v118, v14, s66, v242
	v_fma_f32 v119, v14, s67, v242
	v_fma_f32 v120, v14, s68, v242
	v_fma_f32 v121, v14, s69, v242
	v_fma_f32 v122, v14, s70, v242
	v_fma_f32 v123, v14, s71, v242
	v_fma_f32 v124, v14, s72, v242
	v_fma_f32 v125, v14, s73, v242
	v_fma_f32 v126, v14, s76, v242
	v_fma_f32 v127, v14, s77, v242
	v_fma_f32 v128, v14, s8, v242
	v_fma_f32 v129, v14, s9, v242
	v_fma_f32 v130, v14, s96, v242
	v_fma_f32 v131, v14, s97, v242
	v_fma_f32 v132, v14, s94, v242
	v_fma_f32 v133, v14, s95, v242
	v_fma_f32 v134, v14, s92, v242
	v_fma_f32 v135, v14, s93, v242
	v_fma_f32 v136, v14, s90, v242
	v_fma_f32 v137, v14, s91, v242
	v_fma_f32 v138, v14, s88, v242
	v_fma_f32 v139, v14, s89, v242
	v_fma_f32 v140, v14, s86, v242
	v_fma_f32 v141, v14, s87, v242
	v_fma_f32 v142, v14, s78, v242
	v_fma_f32 v143, v14, s79, v242
	v_exp_f32_e32 v92, v92
	v_exp_f32_e32 v93, v93
	v_add_f32_e32 v240, v106, v240
	v_add_f32_e32 v241, v107, v241
	v_exp_f32_e32 v108, v108
	v_exp_f32_e32 v109, v109
	v_add_f32_e32 v240, v92, v240
	v_add_f32_e32 v241, v93, v241
	v_exp_f32_e32 v94, v94
	v_exp_f32_e32 v95, v95
	v_add_f32_e32 v240, v108, v240
	v_add_f32_e32 v241, v109, v241
	v_exp_f32_e32 v110, v110
	v_exp_f32_e32 v111, v111
	v_add_f32_e32 v240, v94, v240
	v_add_f32_e32 v241, v95, v241
	s_waitcnt lgkmcnt(4)
	v_mfma_f32_32x32x16_bf16 v[112:127], v[160:163], v[2:5], v[112:127]
	v_mfma_f32_32x32x16_bf16 v[112:127], v[164:167], v[6:9], v[112:127]
	v_mfma_f32_32x32x16_bf16 v[112:127], v[168:171], v[10:13], v[112:127]
	v_mfma_f32_32x32x16_bf16 v[112:127], v[172:175], v[144:147], v[112:127]
	ds_read_b128 v[160:163], v251 offset:9216
	ds_read_b128 v[164:167], v251 offset:9248
	ds_read_b128 v[168:171], v251 offset:9280
	ds_read_b128 v[172:175], v251 offset:9312
	s_nop 0
	v_add_f32_e32 v240, v110, v240
	v_add_f32_e32 v241, v111, v241
	v_cvt_pk_bf16_f32 v80, v80, v81
	v_cvt_pk_bf16_f32 v81, v82, v83
	v_cvt_pk_bf16_f32 v82, v84, v85
	v_cvt_pk_bf16_f32 v83, v86, v87
	v_cvt_pk_bf16_f32 v84, v88, v89
	v_cvt_pk_bf16_f32 v85, v90, v91
	v_cvt_pk_bf16_f32 v86, v92, v93
	v_cvt_pk_bf16_f32 v87, v94, v95
	s_waitcnt lgkmcnt(4)
	v_mfma_f32_32x32x16_bf16 v[128:143], v[224:227], v[2:5], v[128:143]
	v_mfma_f32_32x32x16_bf16 v[128:143], v[228:231], v[6:9], v[128:143]
	v_mfma_f32_32x32x16_bf16 v[128:143], v[232:235], v[10:13], v[128:143]
	v_mfma_f32_32x32x16_bf16 v[128:143], v[236:239], v[144:147], v[128:143]
	v_cvt_pk_bf16_f32 v88, v96, v97
	v_cvt_pk_bf16_f32 v89, v98, v99
	v_cvt_pk_bf16_f32 v90, v100, v101
	v_cvt_pk_bf16_f32 v91, v102, v103
	v_cvt_pk_bf16_f32 v92, v104, v105
	v_cvt_pk_bf16_f32 v93, v106, v107
	v_cvt_pk_bf16_f32 v94, v108, v109
	v_cvt_pk_bf16_f32 v95, v110, v111
	v_add_f32_e32 v247, v240, v241
	v_add_f32_e32 v199, v199, v247
	s_branch .Ld_tail0

; #define LAS __attribute__((address_space(3)))
; template <int DQK, int DV, int FLAGS, int qp, int kp, int vts, int op> ...
;     ...
;             if (FLAGS & AF_ALIBI) { const float ab = -slope2 * (float)nrel - ((FLAGS & AF_ROBUST) ? 0.f : m);
; #pragma unroll
;                 for (int r = 0; r < 16; ++r) { const float c = (float)(16 * (r >> 3) + (r & 7)); p0[r] = __builtin_fmaf(slope2, c, ab); p1[r] = __builtin_fmaf(slope2, c + 32.f, ab); }
;             } else if (FLAGS & AF_ROBUST) {
; #pragma unroll
;                 for (int r = 0; r < 16; ++r) { p0[r] = 0.f; p1[r] = 0.f; }
;             } else { p0 = negm; p1 = negm; }
;             __builtin_amdgcn_sched_barrier(0);
; #pragma unroll
;             for (int c = 0; c < ND0 / 2; ++c) {
;                 if (c + 1 < ND0 / 2) {
; #pragma unroll
;                     for (int i = 0; i < 2; ++i) { kf[(c + 1) & 1][2 * i] = *(const LAS bf16x8*)(kb + (2 * c + 2 + i) * 32); kf[(c + 1) & 1][2 * i + 1] = *(const LAS bf16x8*)(kb + 32 * KROW + (2 * c + 2 + i) * 32); }
;                 }
; #pragma unroll
;                 for (int i = 0; i < 2; ++i) {
;                     p0 = __builtin_amdgcn_mfma_f32_32x32x16_bf16(kf[c & 1][2 * i], qr[2 * c + i], p0, 0, 0, 0);
;                     p1 = __builtin_amdgcn_mfma_f32_32x32x16_bf16(kf[c & 1][2 * i + 1], qr[2 * c + i], p1, 0, 0, 0);
;                 }
;                 __builtin_amdgcn_sched_barrier(0);
;             }
;     ...
;             f32x2 rs2 = {0.f, 0.f};
; #pragma unroll
;             for (int r = 0; r < 16; ++r) { p0[r] = __builtin_amdgcn_exp2f(p0[r]); p1[r] = __builtin_amdgcn_exp2f(p1[r]); }
; #pragma unroll
;             for (int r = 0; r < 16; r += 2) { rs2 += (f32x2){p0[r], p0[r + 1]}; rs2 += (f32x2){p1[r], p1[r + 1]}; }
;             l += rs2.x + rs2.y;
;             bf16x8 pf[4];
;             pf[0] = pack_bf16x8(p0, 0); pf[1] = pack_bf16x8(p0, 8); pf[2] = pack_bf16x8(p1, 0); pf[3] = pack_bf16x8(p1, 8);
.Ld_notfirst_p0:
	v_exp_f32_e32 v80, v80
	v_exp_f32_e32 v81, v81
	v_exp_f32_e32 v96, v96
	v_exp_f32_e32 v97, v97
	v_mov_b32_e32 v240, v80
	v_mov_b32_e32 v241, v81
	v_exp_f32_e32 v82, v82
	v_exp_f32_e32 v83, v83
	v_add_f32_e32 v240, v96, v240
	v_add_f32_e32 v241, v97, v241
	v_exp_f32_e32 v98, v98
	v_exp_f32_e32 v99, v99
	v_add_f32_e32 v240, v82, v240
	v_add_f32_e32 v241, v83, v241
	v_exp_f32_e32 v84, v84
	v_exp_f32_e32 v85, v85
	v_add_f32_e32 v240, v98, v240
	v_add_f32_e32 v241, v99, v241
	v_exp_f32_e32 v100, v100
	v_exp_f32_e32 v101, v101
	v_add_f32_e32 v240, v84, v240
	v_add_f32_e32 v241, v85, v241
	v_exp_f32_e32 v86, v86
	v_exp_f32_e32 v87, v87
	v_add_f32_e32 v240, v100, v240
	v_add_f32_e32 v241, v101, v241
	v_exp_f32_e32 v102, v102
	v_exp_f32_e32 v103, v103
	v_add_f32_e32 v240, v86, v240
	v_add_f32_e32 v241, v87, v241
	v_exp_f32_e32 v88, v88
	v_exp_f32_e32 v89, v89
	v_add_f32_e32 v240, v102, v240
	v_add_f32_e32 v241, v103, v241
	v_exp_f32_e32 v104, v104
	v_exp_f32_e32 v105, v105
	v_add_f32_e32 v240, v88, v240
	v_add_f32_e32 v241, v89, v241
	v_exp_f32_e32 v90, v90
	v_exp_f32_e32 v91, v91
	v_add_f32_e32 v240, v104, v240
	v_add_f32_e32 v241, v105, v241
	v_exp_f32_e32 v106, v106
	v_exp_f32_e32 v107, v107
	v_add_f32_e32 v240, v90, v240
	v_add_f32_e32 v241, v91, v241
	v_exp_f32_e32 v92, v92
	v_exp_f32_e32 v93, v93
	v_add_f32_e32 v240, v106, v240
	v_add_f32_e32 v241, v107, v241
	v_exp_f32_e32 v108, v108
	v_exp_f32_e32 v109, v109
	v_add_f32_e32 v240, v92, v240
	v_add_f32_e32 v241, v93, v241
	v_exp_f32_e32 v94, v94
	v_exp_f32_e32 v95, v95
	v_add_f32_e32 v240, v108, v240
	v_add_f32_e32 v241, v109, v241
	v_exp_f32_e32 v110, v110
	v_exp_f32_e32 v111, v111
	v_add_f32_e32 v240, v94, v240
	v_add_f32_e32 v241, v95, v241
	s_nop 0
	v_add_f32_e32 v240, v110, v240
	v_add_f32_e32 v241, v111, v241
	v_cvt_pk_bf16_f32 v80, v80, v81
	v_cvt_pk_bf16_f32 v81, v82, v83
	v_cvt_pk_bf16_f32 v82, v84, v85
	v_cvt_pk_bf16_f32 v83, v86, v87
	v_cvt_pk_bf16_f32 v84, v88, v89
	v_cvt_pk_bf16_f32 v85, v90, v91
	v_cvt_pk_bf16_f32 v86, v92, v93
	v_cvt_pk_bf16_f32 v87, v94, v95
	v_cvt_pk_bf16_f32 v88, v96, v97
	v_cvt_pk_bf16_f32 v89, v98, v99
	v_cvt_pk_bf16_f32 v90, v100, v101
	v_cvt_pk_bf16_f32 v91, v102, v103
	v_cvt_pk_bf16_f32 v92, v104, v105
	v_cvt_pk_bf16_f32 v93, v106, v107
	v_cvt_pk_bf16_f32 v94, v108, v109
	v_cvt_pk_bf16_f32 v95, v110, v111
	v_add_f32_e32 v247, v240, v241
	v_add_f32_e32 v199, v199, v247
.Ld_nosm_p0:
	s_add_i32 s13, s23, 1
	s_cmp_ge_i32 s13, s3
	s_cbranch_scc1 .Ld_noqk_p0
	s_cmp_lt_i32 s13, s24
	s_cbranch_scc1 .Ld_noqk_p0
	s_add_i32 s12, s23, 1
	s_and_b32 s12, s12, 3
	s_mulk_i32 s12, 0x6c00
	v_add3_u32 v244, s12, v201, v194
	ds_read_b128 v[160:163], v244 offset:0
	ds_read_b128 v[164:167], v244 offset:32
	ds_read_b128 v[168:171], v244 offset:64
	ds_read_b128 v[172:175], v244 offset:96
	ds_read_b128 v[224:227], v244 offset:4608
	ds_read_b128 v[228:231], v244 offset:4640
	ds_read_b128 v[232:235], v244 offset:4672
	ds_read_b128 v[236:239], v244 offset:4704
	v_add_u32_e32 v246, 64, v205
	v_cvt_f32_i32_e32 v246, v246
	v_fma_f32 v242, -v14, v246, -v222
	v_mov_b32_e32 v112, v242
	v_add_f32_e32 v113, v14, v242
	v_fma_f32 v114, v14, s62, v242
	v_fma_f32 v115, v14, s63, v242
	v_fma_f32 v116, v14, s64, v242
	v_fma_f32 v117, v14, s65, v242
	v_fma_f32 v118, v14, s66, v242
	v_fma_f32 v119, v14, s67, v242
	v_fma_f32 v120, v14, s68, v242
	v_fma_f32 v121, v14, s69, v242
	v_fma_f32 v122, v14, s70, v242
	v_fma_f32 v123, v14, s71, v242
	v_fma_f32 v124, v14, s72, v242
	v_fma_f32 v125, v14, s73, v242
	v_fma_f32 v126, v14, s76, v242
	v_fma_f32 v127, v14, s77, v242
	v_fma_f32 v128, v14, s8, v242
	v_fma_f32 v129, v14, s9, v242
	v_fma_f32 v130, v14, s96, v242
	v_fma_f32 v131, v14, s97, v242
	v_fma_f32 v132, v14, s94, v242
	v_fma_f32 v133, v14, s95, v242
	v_fma_f32 v134, v14, s92, v242
	v_fma_f32 v135, v14, s93, v242
	v_fma_f32 v136, v14, s90, v242
	v_fma_f32 v137, v14, s91, v242
	v_fma_f32 v138, v14, s88, v242
	v_fma_f32 v139, v14, s89, v242
	v_fma_f32 v140, v14, s86, v242
	v_fma_f32 v141, v14, s87, v242
	v_fma_f32 v142, v14, s78, v242
	v_fma_f32 v143, v14, s79, v242
	s_waitcnt lgkmcnt(0)
	v_mfma_f32_32x32x16_bf16 v[112:127], v[160:163], v[2:5], v[112:127]
	v_mfma_f32_32x32x16_bf16 v[128:143], v[224:227], v[2:5], v[128:143]
	v_mfma_f32_32x32x16_bf16 v[112:127], v[164:167], v[6:9], v[112:127]
	v_mfma_f32_32x32x16_bf16 v[128:143], v[228:231], v[6:9], v[128:143]
	v_mfma_f32_32x32x16_bf16 v[112:127], v[168:171], v[10:13], v[112:127]
	v_mfma_f32_32x32x16_bf16 v[128:143], v[232:235], v[10:13], v[128:143]
	v_mfma_f32_32x32x16_bf16 v[112:127], v[172:175], v[144:147], v[112:127]
	v_mfma_f32_32x32x16_bf16 v[128:143], v[236:239], v[144:147], v[128:143]

; #define LAS __attribute__((address_space(3)))
; template <int DQK, int DV, int FLAGS, int qp, int kp, int vts, int op> ...
;     ...
;             if (FLAGS & AF_ALIBI) { const float ab = -slope2 * (float)nrel - ((FLAGS & AF_ROBUST) ? 0.f : m);
; #pragma unroll
;                 for (int r = 0; r < 16; ++r) { const float c = (float)(16 * (r >> 3) + (r & 7)); p0[r] = __builtin_fmaf(slope2, c, ab); p1[r] = __builtin_fmaf(slope2, c + 32.f, ab); }
;             } else if (FLAGS & AF_ROBUST) {
; #pragma unroll
;                 for (int r = 0; r < 16; ++r) { p0[r] = 0.f; p1[r] = 0.f; }
;             } else { p0 = negm; p1 = negm; }
;             __builtin_amdgcn_sched_barrier(0);
; #pragma unroll
;             for (int c = 0; c < ND0 / 2; ++c) {
;                 if (c + 1 < ND0 / 2) {
; #pragma unroll
;                     for (int i = 0; i < 2; ++i) { kf[(c + 1) & 1][2 * i] = *(const LAS bf16x8*)(kb + (2 * c + 2 + i) * 32); kf[(c + 1) & 1][2 * i + 1] = *(const LAS bf16x8*)(kb + 32 * KROW + (2 * c + 2 + i) * 32); }
;                 }
; #pragma unroll
;                 for (int i = 0; i < 2; ++i) {
;                     p0 = __builtin_amdgcn_mfma_f32_32x32x16_bf16(kf[c & 1][2 * i], qr[2 * c + i], p0, 0, 0, 0);
;                     p1 = __builtin_amdgcn_mfma_f32_32x32x16_bf16(kf[c & 1][2 * i + 1], qr[2 * c + i], p1, 0, 0, 0);
;                 }
;     ...
;             f32x2 rs2 = {0.f, 0.f};
; #pragma unroll
;             for (int r = 0; r < 16; ++r) { p0[r] = __builtin_amdgcn_exp2f(p0[r]); p1[r] = __builtin_amdgcn_exp2f(p1[r]); }
; #pragma unroll
;             for (int r = 0; r < 16; r += 2) { rs2 += (f32x2){p0[r], p0[r + 1]}; rs2 += (f32x2){p1[r], p1[r + 1]}; }
;             l += rs2.x + rs2.y;
;             bf16x8 pf[4];
;             pf[0] = pack_bf16x8(p0, 0); pf[1] = pack_bf16x8(p0, 8); pf[2] = pack_bf16x8(p1, 0); pf[3] = pack_bf16x8(p1, 8);
;             __builtin_amdgcn_sched_barrier(0);
; #pragma unroll
;             for (int d = 0; d < NDB; ++d) {
;                 if (d + 1 < NDB) {
; #pragma unroll
;                     for (int ks = 0; ks < 4; ++ks) vf[(d + 1) & 1][ks] = *(const LAS bf16x8*)(vb + (d + 1) * 32 * VROW + ks * 32);
;                 }
; #pragma unroll
;                 for (int ks = 0; ks < 4; ++ks) o[d] = __builtin_amdgcn_mfma_f32_32x32x16_bf16(vf[d & 1][ks], pf[ks], o[d], 0, 0, 0);
;                 __builtin_amdgcn_sched_barrier(0);
;             }
.Ld_top1:
	s_cmp_le_i32 s23, s24
	s_cbranch_scc1 .Ld_gen1
	s_add_i32 s13, s23, 1
	s_cmp_ge_i32 s13, s3
	s_cbranch_scc1 .Ld_gen1
	s_add_i32 s12, s23, -1
	s_and_b32 s12, s12, 3
	s_mulk_i32 s12, 0x6c00
	v_add3_u32 v245, s12, v203, v194
	ds_read_b128 v[224:227], v245 offset:13824
	ds_read_b128 v[228:231], v245 offset:13856
	ds_read_b128 v[232:235], v245 offset:13888
	ds_read_b128 v[236:239], v245 offset:13920
	s_add_i32 s12, s23, 1
	s_and_b32 s12, s12, 3
	s_mulk_i32 s12, 0x6c00
	v_add3_u32 v244, s12, v201, v194
	s_and_b32 s12, s23, 3
	s_mulk_i32 s12, 0x6c00
	v_add3_u32 v251, s12, v203, v194
	v_mfma_f32_32x32x16_bf16 v[64:79], v[160:163], v[80:83], v[64:79]
	v_mfma_f32_32x32x16_bf16 v[64:79], v[164:167], v[84:87], v[64:79]
	v_mfma_f32_32x32x16_bf16 v[64:79], v[168:171], v[88:91], v[64:79]
	v_mfma_f32_32x32x16_bf16 v[64:79], v[172:175], v[92:95], v[64:79]
	ds_read_b128 v[160:163], v245 offset:18432
	ds_read_b128 v[164:167], v245 offset:18464
	ds_read_b128 v[168:171], v245 offset:18496
	ds_read_b128 v[172:175], v245 offset:18528
	v_exp_f32_e32 v112, v112
	v_exp_f32_e32 v113, v113
	v_exp_f32_e32 v128, v128
	v_exp_f32_e32 v129, v129
	v_mov_b32_e32 v240, v112
	v_mov_b32_e32 v241, v113
	v_exp_f32_e32 v114, v114
	v_exp_f32_e32 v115, v115
	v_add_f32_e32 v240, v128, v240
	v_add_f32_e32 v241, v129, v241
	v_exp_f32_e32 v130, v130
	v_exp_f32_e32 v131, v131
	v_add_f32_e32 v240, v114, v240
	v_add_f32_e32 v241, v115, v241
	s_waitcnt lgkmcnt(4)
	v_mfma_f32_32x32x16_bf16 v[48:63], v[224:227], v[80:83], v[48:63]
	v_mfma_f32_32x32x16_bf16 v[48:63], v[228:231], v[84:87], v[48:63]
	v_mfma_f32_32x32x16_bf16 v[48:63], v[232:235], v[88:91], v[48:63]
	v_mfma_f32_32x32x16_bf16 v[48:63], v[236:239], v[92:95], v[48:63]
	ds_read_b128 v[224:227], v245 offset:23040
	ds_read_b128 v[228:231], v245 offset:23072
	ds_read_b128 v[232:235], v245 offset:23104
	ds_read_b128 v[236:239], v245 offset:23136
	v_exp_f32_e32 v116, v116
	v_exp_f32_e32 v117, v117
	v_add_f32_e32 v240, v130, v240
	v_add_f32_e32 v241, v131, v241
	v_exp_f32_e32 v132, v132
	v_exp_f32_e32 v133, v133
	v_add_f32_e32 v240, v116, v240
	v_add_f32_e32 v241, v117, v241
	v_exp_f32_e32 v118, v118
	v_exp_f32_e32 v119, v119
	v_add_f32_e32 v240, v132, v240
	v_add_f32_e32 v241, v133, v241
	v_exp_f32_e32 v134, v134
	v_exp_f32_e32 v135, v135
	v_add_f32_e32 v240, v118, v240
	v_add_f32_e32 v241, v119, v241
	s_waitcnt lgkmcnt(4)
	v_mfma_f32_32x32x16_bf16 v[32:47], v[160:163], v[80:83], v[32:47]
	v_mfma_f32_32x32x16_bf16 v[32:47], v[164:167], v[84:87], v[32:47]
	v_mfma_f32_32x32x16_bf16 v[32:47], v[168:171], v[88:91], v[32:47]
	v_mfma_f32_32x32x16_bf16 v[32:47], v[172:175], v[92:95], v[32:47]
	ds_read_b128 v[160:163], v244 offset:0
	ds_read_b128 v[164:167], v244 offset:32
	ds_read_b128 v[168:171], v244 offset:64
	ds_read_b128 v[172:175], v244 offset:96
	v_exp_f32_e32 v120, v120
	v_exp_f32_e32 v121, v121
	v_add_f32_e32 v240, v134, v240
	v_add_f32_e32 v241, v135, v241
	v_exp_f32_e32 v136, v136
	v_exp_f32_e32 v137, v137
	v_add_f32_e32 v240, v120, v240
	v_add_f32_e32 v241, v121, v241
	v_exp_f32_e32 v122, v122
	v_exp_f32_e32 v123, v123
	v_add_f32_e32 v240, v136, v240
	v_add_f32_e32 v241, v137, v241
	v_exp_f32_e32 v138, v138
	v_exp_f32_e32 v139, v139
	v_add_f32_e32 v240, v122, v240
	v_add_f32_e32 v241, v123, v241
	s_waitcnt lgkmcnt(4)
	v_mfma_f32_32x32x16_bf16 v[16:31], v[224:227], v[80:83], v[16:31]
	v_mfma_f32_32x32x16_bf16 v[16:31], v[228:231], v[84:87], v[16:31]
	v_mfma_f32_32x32x16_bf16 v[16:31], v[232:235], v[88:91], v[16:31]
	v_mfma_f32_32x32x16_bf16 v[16:31], v[236:239], v[92:95], v[16:31]
	ds_read_b128 v[224:227], v244 offset:4608
	ds_read_b128 v[228:231], v244 offset:4640
	ds_read_b128 v[232:235], v244 offset:4672
	ds_read_b128 v[236:239], v244 offset:4704
	v_add_u32_e32 v246, 64, v205
	v_cvt_f32_i32_e32 v246, v246
	v_fma_f32 v242, -v14, v246, -v222
	v_mov_b32_e32 v80, v242
	v_add_f32_e32 v81, v14, v242
	v_fma_f32 v82, v14, s62, v242
	v_fma_f32 v83, v14, s63, v242
	v_fma_f32 v84, v14, s64, v242
	v_fma_f32 v85, v14, s65, v242
	v_fma_f32 v86, v14, s66, v242
	v_fma_f32 v87, v14, s67, v242
	v_fma_f32 v88, v14, s68, v242
	v_fma_f32 v89, v14, s69, v242
	v_fma_f32 v90, v14, s70, v242
	v_fma_f32 v91, v14, s71, v242
	v_fma_f32 v92, v14, s72, v242
	v_fma_f32 v93, v14, s73, v242
	v_fma_f32 v94, v14, s76, v242
	v_fma_f32 v95, v14, s77, v242
	v_fma_f32 v96, v14, s8, v242
	v_fma_f32 v97, v14, s9, v242
	v_fma_f32 v98, v14, s96, v242
	v_fma_f32 v99, v14, s97, v242
	v_fma_f32 v100, v14, s94, v242
	v_fma_f32 v101, v14, s95, v242
	v_fma_f32 v102, v14, s92, v242
	v_fma_f32 v103, v14, s93, v242
	v_fma_f32 v104, v14, s90, v242
	v_fma_f32 v105, v14, s91, v242
	v_fma_f32 v106, v14, s88, v242
	v_fma_f32 v107, v14, s89, v242
	v_fma_f32 v108, v14, s86, v242
	v_fma_f32 v109, v14, s87, v242
	v_fma_f32 v110, v14, s78, v242
	v_fma_f32 v111, v14, s79, v242
	v_exp_f32_e32 v124, v124
	v_exp_f32_e32 v125, v125
	v_add_f32_e32 v240, v138, v240
	v_add_f32_e32 v241, v139, v241
	v_exp_f32_e32 v140, v140
	v_exp_f32_e32 v141, v141
	v_add_f32_e32 v240, v124, v240
	v_add_f32_e32 v241, v125, v241
	v_exp_f32_e32 v126, v126
	v_exp_f32_e32 v127, v127
	v_add_f32_e32 v240, v140, v240
	v_add_f32_e32 v241, v141, v241
	v_exp_f32_e32 v142, v142
	v_exp_f32_e32 v143, v143
	v_add_f32_e32 v240, v126, v240
	v_add_f32_e32 v241, v127, v241
	s_waitcnt lgkmcnt(4)
	v_mfma_f32_32x32x16_bf16 v[80:95], v[160:163], v[2:5], v[80:95]
	v_mfma_f32_32x32x16_bf16 v[80:95], v[164:167], v[6:9], v[80:95]
	v_mfma_f32_32x32x16_bf16 v[80:95], v[168:171], v[10:13], v[80:95]
	v_mfma_f32_32x32x16_bf16 v[80:95], v[172:175], v[144:147], v[80:95]
	ds_read_b128 v[160:163], v251 offset:9216
	ds_read_b128 v[164:167], v251 offset:9248
	ds_read_b128 v[168:171], v251 offset:9280
	ds_read_b128 v[172:175], v251 offset:9312
	s_nop 0
	v_add_f32_e32 v240, v142, v240
	v_add_f32_e32 v241, v143, v241
	v_cvt_pk_bf16_f32 v112, v112, v113
	v_cvt_pk_bf16_f32 v113, v114, v115
	v_cvt_pk_bf16_f32 v114, v116, v117
	v_cvt_pk_bf16_f32 v115, v118, v119
	v_cvt_pk_bf16_f32 v116, v120, v121
	v_cvt_pk_bf16_f32 v117, v122, v123
	v_cvt_pk_bf16_f32 v118, v124, v125
	v_cvt_pk_bf16_f32 v119, v126, v127
	s_waitcnt lgkmcnt(4)
	v_mfma_f32_32x32x16_bf16 v[96:111], v[224:227], v[2:5], v[96:111]
	v_mfma_f32_32x32x16_bf16 v[96:111], v[228:231], v[6:9], v[96:111]
	v_mfma_f32_32x32x16_bf16 v[96:111], v[232:235], v[10:13], v[96:111]
	v_mfma_f32_32x32x16_bf16 v[96:111], v[236:239], v[144:147], v[96:111]
	v_cvt_pk_bf16_f32 v120, v128, v129
	v_cvt_pk_bf16_f32 v121, v130, v131
	v_cvt_pk_bf16_f32 v122, v132, v133
	v_cvt_pk_bf16_f32 v123, v134, v135
	v_cvt_pk_bf16_f32 v124, v136, v137
	v_cvt_pk_bf16_f32 v125, v138, v139
	v_cvt_pk_bf16_f32 v126, v140, v141
	v_cvt_pk_bf16_f32 v127, v142, v143
	v_add_f32_e32 v247, v240, v241
	v_add_f32_e32 v199, v199, v247
	s_branch .Ld_tail1

; #define LAS __attribute__((address_space(3)))
; template <int DQK, int DV, int FLAGS, int qp, int kp, int vts, int op> ...
;     ...
;             if (FLAGS & AF_ALIBI) { const float ab = -slope2 * (float)nrel - ((FLAGS & AF_ROBUST) ? 0.f : m);
; #pragma unroll
;                 for (int r = 0; r < 16; ++r) { const float c = (float)(16 * (r >> 3) + (r & 7)); p0[r] = __builtin_fmaf(slope2, c, ab); p1[r] = __builtin_fmaf(slope2, c + 32.f, ab); }
;             } else if (FLAGS & AF_ROBUST) {
; #pragma unroll
;                 for (int r = 0; r < 16; ++r) { p0[r] = 0.f; p1[r] = 0.f; }
;             } else { p0 = negm; p1 = negm; }
;             __builtin_amdgcn_sched_barrier(0);
; #pragma unroll
;             for (int c = 0; c < ND0 / 2; ++c) {
;                 if (c + 1 < ND0 / 2) {
; #pragma unroll
;                     for (int i = 0; i < 2; ++i) { kf[(c + 1) & 1][2 * i] = *(const LAS bf16x8*)(kb + (2 * c + 2 + i) * 32); kf[(c + 1) & 1][2 * i + 1] = *(const LAS bf16x8*)(kb + 32 * KROW + (2 * c + 2 + i) * 32); }
;                 }
; #pragma unroll
;                 for (int i = 0; i < 2; ++i) {
;                     p0 = __builtin_amdgcn_mfma_f32_32x32x16_bf16(kf[c & 1][2 * i], qr[2 * c + i], p0, 0, 0, 0);
;                     p1 = __builtin_amdgcn_mfma_f32_32x32x16_bf16(kf[c & 1][2 * i + 1], qr[2 * c + i], p1, 0, 0, 0);
;                 }
;                 __builtin_amdgcn_sched_barrier(0);
;             }
;     ...
;             f32x2 rs2 = {0.f, 0.f};
; #pragma unroll
;             for (int r = 0; r < 16; ++r) { p0[r] = __builtin_amdgcn_exp2f(p0[r]); p1[r] = __builtin_amdgcn_exp2f(p1[r]); }
; #pragma unroll
;             for (int r = 0; r < 16; r += 2) { rs2 += (f32x2){p0[r], p0[r + 1]}; rs2 += (f32x2){p1[r], p1[r + 1]}; }
;             l += rs2.x + rs2.y;
;             bf16x8 pf[4];
;             pf[0] = pack_bf16x8(p0, 0); pf[1] = pack_bf16x8(p0, 8); pf[2] = pack_bf16x8(p1, 0); pf[3] = pack_bf16x8(p1, 8);
.Ld_notfirst_p1:
	v_exp_f32_e32 v112, v112
	v_exp_f32_e32 v113, v113
	v_exp_f32_e32 v128, v128
	v_exp_f32_e32 v129, v129
	v_mov_b32_e32 v240, v112
	v_mov_b32_e32 v241, v113
	v_exp_f32_e32 v114, v114
	v_exp_f32_e32 v115, v115
	v_add_f32_e32 v240, v128, v240
	v_add_f32_e32 v241, v129, v241
	v_exp_f32_e32 v130, v130
	v_exp_f32_e32 v131, v131
	v_add_f32_e32 v240, v114, v240
	v_add_f32_e32 v241, v115, v241
	v_exp_f32_e32 v116, v116
	v_exp_f32_e32 v117, v117
	v_add_f32_e32 v240, v130, v240
	v_add_f32_e32 v241, v131, v241
	v_exp_f32_e32 v132, v132
	v_exp_f32_e32 v133, v133
	v_add_f32_e32 v240, v116, v240
	v_add_f32_e32 v241, v117, v241
	v_exp_f32_e32 v118, v118
	v_exp_f32_e32 v119, v119
	v_add_f32_e32 v240, v132, v240
	v_add_f32_e32 v241, v133, v241
	v_exp_f32_e32 v134, v134
	v_exp_f32_e32 v135, v135
	v_add_f32_e32 v240, v118, v240
	v_add_f32_e32 v241, v119, v241
	v_exp_f32_e32 v120, v120
	v_exp_f32_e32 v121, v121
	v_add_f32_e32 v240, v134, v240
	v_add_f32_e32 v241, v135, v241
	v_exp_f32_e32 v136, v136
	v_exp_f32_e32 v137, v137
	v_add_f32_e32 v240, v120, v240
	v_add_f32_e32 v241, v121, v241
	v_exp_f32_e32 v122, v122
	v_exp_f32_e32 v123, v123
	v_add_f32_e32 v240, v136, v240
	v_add_f32_e32 v241, v137, v241
	v_exp_f32_e32 v138, v138
	v_exp_f32_e32 v139, v139
	v_add_f32_e32 v240, v122, v240
	v_add_f32_e32 v241, v123, v241
	v_exp_f32_e32 v124, v124
	v_exp_f32_e32 v125, v125
	v_add_f32_e32 v240, v138, v240
	v_add_f32_e32 v241, v139, v241
	v_exp_f32_e32 v140, v140
	v_exp_f32_e32 v141, v141
	v_add_f32_e32 v240, v124, v240
	v_add_f32_e32 v241, v125, v241
	v_exp_f32_e32 v126, v126
	v_exp_f32_e32 v127, v127
	v_add_f32_e32 v240, v140, v240
	v_add_f32_e32 v241, v141, v241
	v_exp_f32_e32 v142, v142
	v_exp_f32_e32 v143, v143
	v_add_f32_e32 v240, v126, v240
	v_add_f32_e32 v241, v127, v241
	s_nop 0
	v_add_f32_e32 v240, v142, v240
	v_add_f32_e32 v241, v143, v241
	v_cvt_pk_bf16_f32 v112, v112, v113
	v_cvt_pk_bf16_f32 v113, v114, v115
	v_cvt_pk_bf16_f32 v114, v116, v117
	v_cvt_pk_bf16_f32 v115, v118, v119
	v_cvt_pk_bf16_f32 v116, v120, v121
	v_cvt_pk_bf16_f32 v117, v122, v123
	v_cvt_pk_bf16_f32 v118, v124, v125
	v_cvt_pk_bf16_f32 v119, v126, v127
	v_cvt_pk_bf16_f32 v120, v128, v129
	v_cvt_pk_bf16_f32 v121, v130, v131
	v_cvt_pk_bf16_f32 v122, v132, v133
	v_cvt_pk_bf16_f32 v123, v134, v135
	v_cvt_pk_bf16_f32 v124, v136, v137
	v_cvt_pk_bf16_f32 v125, v138, v139
	v_cvt_pk_bf16_f32 v126, v140, v141
	v_cvt_pk_bf16_f32 v127, v142, v143
	v_add_f32_e32 v247, v240, v241
	v_add_f32_e32 v199, v199, v247
.Ld_nosm_p1:
	s_add_i32 s13, s23, 1
	s_cmp_ge_i32 s13, s3
	s_cbranch_scc1 .Ld_noqk_p1
	s_cmp_lt_i32 s13, s24
	s_cbranch_scc1 .Ld_noqk_p1
	s_add_i32 s12, s23, 1
	s_and_b32 s12, s12, 3
	s_mulk_i32 s12, 0x6c00
	v_add3_u32 v244, s12, v201, v194
	ds_read_b128 v[160:163], v244 offset:0
	ds_read_b128 v[164:167], v244 offset:32
	ds_read_b128 v[168:171], v244 offset:64
	ds_read_b128 v[172:175], v244 offset:96
	ds_read_b128 v[224:227], v244 offset:4608
	ds_read_b128 v[228:231], v244 offset:4640
	ds_read_b128 v[232:235], v244 offset:4672
	ds_read_b128 v[236:239], v244 offset:4704
	v_add_u32_e32 v246, 64, v205
	v_cvt_f32_i32_e32 v246, v246
	v_fma_f32 v242, -v14, v246, -v222
	v_mov_b32_e32 v80, v242
	v_add_f32_e32 v81, v14, v242
	v_fma_f32 v82, v14, s62, v242
	v_fma_f32 v83, v14, s63, v242
	v_fma_f32 v84, v14, s64, v242
	v_fma_f32 v85, v14, s65, v242
	v_fma_f32 v86, v14, s66, v242
	v_fma_f32 v87, v14, s67, v242
	v_fma_f32 v88, v14, s68, v242
	v_fma_f32 v89, v14, s69, v242
	v_fma_f32 v90, v14, s70, v242
	v_fma_f32 v91, v14, s71, v242
	v_fma_f32 v92, v14, s72, v242
	v_fma_f32 v93, v14, s73, v242
	v_fma_f32 v94, v14, s76, v242
	v_fma_f32 v95, v14, s77, v242
	v_fma_f32 v96, v14, s8, v242
	v_fma_f32 v97, v14, s9, v242
	v_fma_f32 v98, v14, s96, v242
	v_fma_f32 v99, v14, s97, v242
	v_fma_f32 v100, v14, s94, v242
	v_fma_f32 v101, v14, s95, v242
	v_fma_f32 v102, v14, s92, v242
	v_fma_f32 v103, v14, s93, v242
	v_fma_f32 v104, v14, s90, v242
	v_fma_f32 v105, v14, s91, v242
	v_fma_f32 v106, v14, s88, v242
	v_fma_f32 v107, v14, s89, v242
	v_fma_f32 v108, v14, s86, v242
	v_fma_f32 v109, v14, s87, v242
	v_fma_f32 v110, v14, s78, v242
	v_fma_f32 v111, v14, s79, v242
	s_waitcnt lgkmcnt(0)
	v_mfma_f32_32x32x16_bf16 v[80:95], v[160:163], v[2:5], v[80:95]
	v_mfma_f32_32x32x16_bf16 v[96:111], v[224:227], v[2:5], v[96:111]
	v_mfma_f32_32x32x16_bf16 v[80:95], v[164:167], v[6:9], v[80:95]
	v_mfma_f32_32x32x16_bf16 v[96:111], v[228:231], v[6:9], v[96:111]
	v_mfma_f32_32x32x16_bf16 v[80:95], v[168:171], v[10:13], v[80:95]
	v_mfma_f32_32x32x16_bf16 v[96:111], v[232:235], v[10:13], v[96:111]
	v_mfma_f32_32x32x16_bf16 v[80:95], v[172:175], v[144:147], v[80:95]
	v_mfma_f32_32x32x16_bf16 v[96:111], v[236:239], v[144:147], v[96:111]
